# v9: v3 + K-loop waits of each unit's first two phases no longer drain the previous epilogue's stores (prologue drains fully instead)
# baseline (speedup 1.0000x reference)
.LBB0_486:
	s_add_u32 s10, s10, 0x1b800000
	v_and_b32_e32 v4, 48, v10
	v_lshlrev_b32_e32 v5, 6, v10
	s_movk_i32 s12, 0x3c0
	s_addc_u32 s11, s11, 0
	s_lshl_b32 s40, s7, 6
	s_lshl_b32 s7, s7, 13
	v_and_or_b32 v4, v5, s12, v4
	v_and_b32_e32 v2, 32, v2
	v_bitop3_b32 v5, v4, s7, v2 bitop3:0xde
	s_lshl_b32 s7, s15, 5
	s_and_b32 s41, s7, 0x60
	s_lshl_b32 s7, s41, 7
	v_bitop3_b32 v174, s7, v4, v2 bitop3:0xf6
	v_lshlrev_b32_e32 v2, 14, v11
	v_and_b32_e32 v2, 0xffff8000, v2
	v_lshl_add_u32 v2, v12, 11, v2
	v_and_b32_e32 v4, 1, v11
	v_lshl_or_b32 v2, v4, 6, v2
	v_lshl_add_u32 v170, v13, 1, v2
	v_lshlrev_b32_e32 v2, 14, v14
	v_and_b32_e32 v2, 0xffff8000, v2
	s_waitcnt vmcnt(0)
	v_lshl_add_u32 v2, v15, 11, v2
	v_and_b32_e32 v4, 1, v14
	s_cmpk_lt_u32 s14, 0x100
	v_lshl_or_b32 v2, v4, 6, v2
	s_cselect_b64 s[12:13], -1, 0
	v_mov_b32_e32 v171, v3
	v_lshl_add_u32 v172, v16, 1, v2
	v_mov_b32_e32 v173, v3
	s_mov_b32 s7, 0
	v_add_u32_e32 v175, 0, v5
	s_mov_b32 s28, 0
	s_barrier
	s_branch .LBB0_489

.LBB0_491:
	s_ashr_i32 s17, s16, 31
	s_lshl_b64 s[18:19], s[16:17], 19
	s_add_u32 s17, s3, s18
	s_addc_u32 s20, s30, s19
	s_ashr_i32 s15, s14, 31
	s_lshl_b64 s[18:19], s[14:15], 19
	s_add_u32 s15, s31, s18
	s_addc_u32 s23, s34, s19
	s_add_i32 s29, 0, 0x10000
	s_and_b64 s[18:19], s[38:39], exec
	s_cselect_b32 s19, s20, s27
	s_cselect_b32 s18, s17, s26
	s_add_i32 s58, 0, 0x14000
	v_add_u32_e32 v2, s29, v174
	v_add_u32_e32 v85, s58, v174
	ds_read_b128 v[4:7], v2
	ds_read_b128 v[8:11], v2 offset:1024
	ds_read_b128 v[12:15], v2 offset:2048
	ds_read_b128 v[16:19], v2 offset:3072
	ds_read_b128 v[20:23], v85
	ds_read_b128 v[24:27], v85 offset:1024
	ds_read_b128 v[28:31], v85 offset:2048
	ds_read_b128 v[32:35], v85 offset:3072
	s_and_b64 s[20:21], s[38:39], exec
	s_cselect_b32 s21, s23, s25
	s_cselect_b32 s20, s15, s24
	s_add_u32 s54, s26, 0x40080
	s_addc_u32 s55, s27, 0
	s_add_i32 s15, s44, 0xc000
	v_lshl_add_u64 v[68:69], s[54:55], 0, v[0:1]
	s_mov_b32 m0, s15
	s_add_i32 s17, s44, 0xe000
	ds_read_b128 v[36:39], v175
	ds_read_b128 v[40:43], v175 offset:1024
	ds_read_b128 v[44:47], v175 offset:2048
	ds_read_b128 v[48:51], v175 offset:3072
	ds_read_b128 v[52:55], v175 offset:4096
	ds_read_b128 v[56:59], v175 offset:5120
	ds_read_b128 v[60:63], v175 offset:6144
	ds_read_b128 v[64:67], v175 offset:7168
	global_load_lds_dwordx4 v[68:69], off
	v_lshl_add_u64 v[68:69], s[54:55], 0, v[166:167]
	s_mov_b32 m0, s17
	s_nop 0
	global_load_lds_dwordx4 v[68:69], off
	s_waitcnt vmcnt(17)
	s_waitcnt lgkmcnt(0)
	s_setprio 1
	s_barrier
	v_mfma_f32_16x16x32_bf16 v[68:71], v[4:7], v[36:39], 0
	v_mfma_f32_16x16x32_bf16 v[72:75], v[12:15], v[36:39], 0
	v_mfma_f32_16x16x32_bf16 v[80:83], v[12:15], v[44:47], 0
	v_mfma_f32_16x16x32_bf16 v[76:79], v[4:7], v[44:47], 0
	v_mfma_f32_16x16x32_bf16 v[86:89], v[4:7], v[52:55], 0
	v_mfma_f32_16x16x32_bf16 v[68:71], v[8:11], v[40:43], v[68:71]
	v_mfma_f32_16x16x32_bf16 v[72:75], v[16:19], v[40:43], v[72:75]
	v_mfma_f32_16x16x32_bf16 v[140:143], v[8:11], v[48:51], v[76:79]
	v_mfma_f32_16x16x32_bf16 v[80:83], v[16:19], v[48:51], v[80:83]
	v_mfma_f32_16x16x32_bf16 v[144:147], v[8:11], v[56:59], v[86:89]
	v_mfma_f32_16x16x32_bf16 v[92:95], v[12:15], v[52:55], 0
	v_mfma_f32_16x16x32_bf16 v[96:99], v[4:7], v[60:63], 0
	v_mfma_f32_16x16x32_bf16 v[100:103], v[12:15], v[60:63], 0
	v_mfma_f32_16x16x32_bf16 v[92:95], v[16:19], v[56:59], v[92:95]
	v_mfma_f32_16x16x32_bf16 v[96:99], v[8:11], v[64:67], v[96:99]
	v_mfma_f32_16x16x32_bf16 v[100:103], v[16:19], v[64:67], v[100:103]
	v_mfma_f32_16x16x32_bf16 v[104:107], v[20:23], v[36:39], 0
	v_mfma_f32_16x16x32_bf16 v[36:39], v[28:31], v[36:39], 0
	v_mfma_f32_16x16x32_bf16 v[104:107], v[24:27], v[40:43], v[104:107]
	v_mfma_f32_16x16x32_bf16 v[36:39], v[32:35], v[40:43], v[36:39]
	v_mfma_f32_16x16x32_bf16 v[40:43], v[20:23], v[44:47], 0
	v_mfma_f32_16x16x32_bf16 v[44:47], v[28:31], v[44:47], 0
	v_mfma_f32_16x16x32_bf16 v[40:43], v[24:27], v[48:51], v[40:43]
	v_mfma_f32_16x16x32_bf16 v[44:47], v[32:35], v[48:51], v[44:47]
	v_mfma_f32_16x16x32_bf16 v[48:51], v[20:23], v[52:55], 0
	v_mfma_f32_16x16x32_bf16 v[52:55], v[28:31], v[52:55], 0
	v_mfma_f32_16x16x32_bf16 v[48:51], v[24:27], v[56:59], v[48:51]
	v_mfma_f32_16x16x32_bf16 v[52:55], v[32:35], v[56:59], v[52:55]
	v_mfma_f32_16x16x32_bf16 v[56:59], v[20:23], v[60:63], 0
	v_mfma_f32_16x16x32_bf16 v[60:63], v[28:31], v[60:63], 0
	v_mfma_f32_16x16x32_bf16 v[56:59], v[24:27], v[64:67], v[56:59]
	v_mfma_f32_16x16x32_bf16 v[60:63], v[32:35], v[64:67], v[60:63]
	s_barrier
	s_setprio 0
	s_add_i32 s23, s29, s0
	v_lshl_add_u64 v[192:193], s[24:25], 0, v[164:165]
	s_mov_b64 s[60:61], 0x100
	s_add_i32 s53, s23, 0x2000
	v_lshl_add_u64 v[76:77], v[192:193], 0, s[60:61]
	s_mov_b32 m0, s23
	v_lshl_add_u64 v[198:199], s[24:25], 0, v[168:169]
	s_add_u32 s56, s24, 0x40100
	ds_read_b128 v[64:67], v175 offset:16384
	ds_read_b128 v[108:111], v175 offset:17408
	ds_read_b128 v[112:115], v175 offset:18432
	ds_read_b128 v[116:119], v175 offset:19456
	ds_read_b128 v[120:123], v175 offset:20480
	ds_read_b128 v[124:127], v175 offset:21504
	ds_read_b128 v[128:131], v175 offset:22528
	ds_read_b128 v[132:135], v175 offset:23552
	global_load_lds_dwordx4 v[76:77], off
	v_lshl_add_u64 v[76:77], v[198:199], 0, s[60:61]
	s_mov_b32 m0, s53
	s_addc_u32 s57, s25, 0
	s_add_i32 s54, s58, s0
	global_load_lds_dwordx4 v[76:77], off
	v_lshl_add_u64 v[76:77], s[56:57], 0, v[164:165]
	s_mov_b32 m0, s54
	s_add_i32 s55, s54, 0x2000
	global_load_lds_dwordx4 v[76:77], off
	v_lshl_add_u64 v[76:77], s[56:57], 0, v[168:169]
	s_mov_b32 m0, s55
	v_lshl_add_u64 v[228:229], s[26:27], 0, v[0:1]
	global_load_lds_dwordx4 v[76:77], off
	v_lshl_add_u64 v[76:77], v[228:229], 0, s[60:61]
	s_mov_b32 m0, s44
	v_lshl_add_u64 v[234:235], s[26:27], 0, v[166:167]
	global_load_lds_dwordx4 v[76:77], off
	v_lshl_add_u64 v[76:77], v[234:235], 0, s[60:61]
	s_mov_b32 m0, s45
	s_nop 0
	global_load_lds_dwordx4 v[76:77], off
	s_waitcnt vmcnt(17)
	s_waitcnt lgkmcnt(0)
	s_setprio 1
	s_barrier
	v_mfma_f32_16x16x32_bf16 v[136:139], v[4:7], v[64:67], 0
	s_nop 0
	v_mfma_f32_16x16x32_bf16 v[176:179], v[8:11], v[108:111], v[136:139]
	v_mfma_f32_16x16x32_bf16 v[136:139], v[12:15], v[64:67], 0
	s_nop 0
	v_mfma_f32_16x16x32_bf16 v[180:183], v[16:19], v[108:111], v[136:139]
	v_mfma_f32_16x16x32_bf16 v[136:139], v[4:7], v[112:115], 0
	s_nop 0
	v_mfma_f32_16x16x32_bf16 v[184:187], v[8:11], v[116:119], v[136:139]
	v_mfma_f32_16x16x32_bf16 v[136:139], v[12:15], v[112:115], 0
	s_nop 0
	v_mfma_f32_16x16x32_bf16 v[200:203], v[16:19], v[116:119], v[136:139]
	v_mfma_f32_16x16x32_bf16 v[136:139], v[4:7], v[120:123], 0
	v_mfma_f32_16x16x32_bf16 v[4:7], v[4:7], v[128:131], 0
	v_mfma_f32_16x16x32_bf16 v[204:207], v[8:11], v[124:127], v[136:139]
	v_mfma_f32_16x16x32_bf16 v[4:7], v[8:11], v[132:135], v[4:7]
	v_mfma_f32_16x16x32_bf16 v[8:11], v[12:15], v[128:131], 0
	v_mfma_f32_16x16x32_bf16 v[136:139], v[12:15], v[120:123], 0
	v_mfma_f32_16x16x32_bf16 v[12:15], v[16:19], v[132:135], v[8:11]
	v_mfma_f32_16x16x32_bf16 v[208:211], v[16:19], v[124:127], v[136:139]
	v_mfma_f32_16x16x32_bf16 v[8:11], v[20:23], v[64:67], 0
	s_nop 0
	v_mfma_f32_16x16x32_bf16 v[16:19], v[24:27], v[108:111], v[8:11]
	v_mfma_f32_16x16x32_bf16 v[8:11], v[28:31], v[64:67], 0
	s_nop 0
	v_mfma_f32_16x16x32_bf16 v[108:111], v[32:35], v[108:111], v[8:11]
	v_mfma_f32_16x16x32_bf16 v[8:11], v[20:23], v[112:115], 0
	s_nop 0
	v_mfma_f32_16x16x32_bf16 v[212:215], v[24:27], v[116:119], v[8:11]
	v_mfma_f32_16x16x32_bf16 v[8:11], v[28:31], v[112:115], 0
	s_nop 0
	v_mfma_f32_16x16x32_bf16 v[112:115], v[32:35], v[116:119], v[8:11]
	v_mfma_f32_16x16x32_bf16 v[8:11], v[20:23], v[120:123], 0
	s_nop 0
	v_mfma_f32_16x16x32_bf16 v[216:219], v[24:27], v[124:127], v[8:11]
	v_mfma_f32_16x16x32_bf16 v[8:11], v[28:31], v[120:123], 0
	s_nop 0
	v_mfma_f32_16x16x32_bf16 v[220:223], v[32:35], v[124:127], v[8:11]
	v_mfma_f32_16x16x32_bf16 v[8:11], v[20:23], v[128:131], 0
	s_nop 0
	v_mfma_f32_16x16x32_bf16 v[236:239], v[24:27], v[132:135], v[8:11]
	v_mfma_f32_16x16x32_bf16 v[8:11], v[28:31], v[128:131], 0
	s_nop 0
	v_mfma_f32_16x16x32_bf16 v[240:243], v[32:35], v[132:135], v[8:11]
	s_barrier
	s_setprio 0
	s_add_i32 s29, 0, 0x18000
	s_add_i32 s58, 0, 0x1c000
	v_add_u32_e32 v86, s29, v174
	v_add_u32_e32 v87, s58, v174
	ds_read_b128 v[8:11], v86
	ds_read_b128 v[28:31], v86 offset:1024
	ds_read_b128 v[32:35], v86 offset:2048
	ds_read_b128 v[64:67], v86 offset:3072
	ds_read_b128 v[244:247], v87
	ds_read_b128 v[248:251], v87 offset:1024
	ds_read_b128 v[230:233], v87 offset:2048
	ds_read_b128 v[194:197], v87 offset:3072
	s_add_u32 s56, s26, 0x40100
	s_addc_u32 s57, s27, 0
	s_mov_b32 m0, s46
	v_lshl_add_u64 v[116:117], s[56:57], 0, v[0:1]
	ds_read_b128 v[20:23], v175 offset:32768
	ds_read_b128 v[24:27], v175 offset:33792
	ds_read_b128 v[124:127], v175 offset:34816
	ds_read_b128 v[128:131], v175 offset:35840
	ds_read_b128 v[224:227], v175 offset:36864
	ds_read_b128 v[188:191], v175 offset:37888
	ds_read_b128 v[76:79], v175 offset:38912
	ds_read_b128 v[88:91], v175 offset:39936
	global_load_lds_dwordx4 v[116:117], off
	v_lshl_add_u64 v[116:117], s[56:57], 0, v[166:167]
	s_mov_b32 m0, s48
	s_nop 0
	global_load_lds_dwordx4 v[116:117], off
	s_waitcnt vmcnt(8)
	s_waitcnt lgkmcnt(0)
	s_setprio 1
	s_barrier
	v_mfma_f32_16x16x32_bf16 v[68:71], v[8:11], v[20:23], v[68:71]
	v_mfma_f32_16x16x32_bf16 v[152:155], v[28:31], v[24:27], v[68:71]
	v_mfma_f32_16x16x32_bf16 v[68:71], v[32:35], v[20:23], v[72:75]
	v_mfma_f32_16x16x32_bf16 v[148:151], v[64:67], v[24:27], v[68:71]
	v_mfma_f32_16x16x32_bf16 v[68:71], v[8:11], v[124:127], v[140:143]
	v_mfma_f32_16x16x32_bf16 v[136:139], v[28:31], v[128:131], v[68:71]
	v_mfma_f32_16x16x32_bf16 v[68:71], v[32:35], v[124:127], v[80:83]
	v_mfma_f32_16x16x32_bf16 v[132:135], v[64:67], v[128:131], v[68:71]
	v_mfma_f32_16x16x32_bf16 v[68:71], v[8:11], v[224:227], v[144:147]
	v_mfma_f32_16x16x32_bf16 v[120:123], v[28:31], v[188:191], v[68:71]
	v_mfma_f32_16x16x32_bf16 v[68:71], v[32:35], v[224:227], v[92:95]
	v_mfma_f32_16x16x32_bf16 v[116:119], v[64:67], v[188:191], v[68:71]
	v_mfma_f32_16x16x32_bf16 v[68:71], v[8:11], v[76:79], v[96:99]
	v_mfma_f32_16x16x32_bf16 v[72:75], v[28:31], v[88:91], v[68:71]
	v_mfma_f32_16x16x32_bf16 v[68:71], v[32:35], v[76:79], v[100:103]
	v_mfma_f32_16x16x32_bf16 v[68:71], v[64:67], v[88:91], v[68:71]
	v_mfma_f32_16x16x32_bf16 v[80:83], v[244:247], v[20:23], v[104:107]
	v_mfma_f32_16x16x32_bf16 v[20:23], v[230:233], v[20:23], v[36:39]
	v_mfma_f32_16x16x32_bf16 v[156:159], v[194:197], v[24:27], v[20:23]
	v_mfma_f32_16x16x32_bf16 v[20:23], v[244:247], v[124:127], v[40:43]
	v_mfma_f32_16x16x32_bf16 v[144:147], v[248:251], v[128:131], v[20:23]
	v_mfma_f32_16x16x32_bf16 v[20:23], v[230:233], v[124:127], v[44:47]
	v_mfma_f32_16x16x32_bf16 v[140:143], v[194:197], v[128:131], v[20:23]
	v_mfma_f32_16x16x32_bf16 v[20:23], v[244:247], v[224:227], v[48:51]
	v_mfma_f32_16x16x32_bf16 v[128:131], v[248:251], v[188:191], v[20:23]
	v_mfma_f32_16x16x32_bf16 v[20:23], v[230:233], v[224:227], v[52:55]
	v_mfma_f32_16x16x32_bf16 v[124:127], v[194:197], v[188:191], v[20:23]
	v_mfma_f32_16x16x32_bf16 v[20:23], v[244:247], v[76:79], v[56:59]
	v_mfma_f32_16x16x32_bf16 v[160:163], v[248:251], v[24:27], v[80:83]
	v_mfma_f32_16x16x32_bf16 v[80:83], v[248:251], v[88:91], v[20:23]
	v_mfma_f32_16x16x32_bf16 v[20:23], v[230:233], v[76:79], v[60:63]
	v_mfma_f32_16x16x32_bf16 v[76:79], v[194:197], v[88:91], v[20:23]
	s_barrier
	s_setprio 0
	s_add_i32 s56, s29, s0
	s_add_i32 s57, s56, 0x2000
	s_nop 2
	v_lshl_add_u64 v[20:21], v[192:193], 0, s[84:85]
	s_mov_b32 m0, s56
	s_add_u32 s60, s24, 0x40180
	ds_read_b128 v[44:47], v175 offset:49152
	ds_read_b128 v[48:51], v175 offset:50176
	ds_read_b128 v[88:91], v175 offset:51200
	ds_read_b128 v[92:95], v175 offset:52224
	ds_read_b128 v[96:99], v175 offset:53248
	ds_read_b128 v[100:103], v175 offset:54272
	ds_read_b128 v[104:107], v175 offset:55296
	ds_read_b128 v[188:191], v175 offset:56320
	global_load_lds_dwordx4 v[20:21], off
	v_lshl_add_u64 v[20:21], v[198:199], 0, s[84:85]
	s_mov_b32 m0, s57
	s_addc_u32 s61, s25, 0
	s_add_i32 s58, s58, s0
	global_load_lds_dwordx4 v[20:21], off
	v_lshl_add_u64 v[20:21], s[60:61], 0, v[164:165]
	s_mov_b32 m0, s58
	s_add_i32 s59, s58, 0x2000
	global_load_lds_dwordx4 v[20:21], off
	v_lshl_add_u64 v[20:21], s[60:61], 0, v[168:169]
	s_mov_b32 m0, s59
	s_nop 0
	global_load_lds_dwordx4 v[20:21], off
	v_lshl_add_u64 v[20:21], v[228:229], 0, s[84:85]
	s_mov_b32 m0, s49
	s_nop 0
	global_load_lds_dwordx4 v[20:21], off
	v_lshl_add_u64 v[20:21], v[234:235], 0, s[84:85]
	s_mov_b32 m0, s50
	s_nop 0
	global_load_lds_dwordx4 v[20:21], off
	s_waitcnt vmcnt(8)
	s_waitcnt lgkmcnt(0)
	s_setprio 1
	s_barrier
	v_mfma_f32_16x16x32_bf16 v[20:23], v[8:11], v[44:47], v[176:179]
	v_mfma_f32_16x16x32_bf16 v[56:59], v[28:31], v[48:51], v[20:23]
	v_mfma_f32_16x16x32_bf16 v[20:23], v[32:35], v[44:47], v[180:183]
	v_mfma_f32_16x16x32_bf16 v[52:55], v[64:67], v[48:51], v[20:23]
	v_mfma_f32_16x16x32_bf16 v[20:23], v[8:11], v[88:91], v[184:187]
	v_mfma_f32_16x16x32_bf16 v[40:43], v[28:31], v[92:95], v[20:23]
	v_mfma_f32_16x16x32_bf16 v[20:23], v[32:35], v[88:91], v[200:203]
	v_mfma_f32_16x16x32_bf16 v[36:39], v[64:67], v[92:95], v[20:23]
	v_mfma_f32_16x16x32_bf16 v[20:23], v[8:11], v[96:99], v[204:207]
	v_mfma_f32_16x16x32_bf16 v[4:7], v[8:11], v[104:107], v[4:7]
	v_mfma_f32_16x16x32_bf16 v[24:27], v[28:31], v[100:103], v[20:23]
	v_mfma_f32_16x16x32_bf16 v[20:23], v[32:35], v[96:99], v[208:211]
	v_mfma_f32_16x16x32_bf16 v[8:11], v[28:31], v[188:191], v[4:7]
	v_mfma_f32_16x16x32_bf16 v[4:7], v[32:35], v[104:107], v[12:15]
	v_mfma_f32_16x16x32_bf16 v[20:23], v[64:67], v[100:103], v[20:23]
	v_mfma_f32_16x16x32_bf16 v[4:7], v[64:67], v[188:191], v[4:7]
	v_mfma_f32_16x16x32_bf16 v[12:15], v[244:247], v[44:47], v[16:19]
	v_mfma_f32_16x16x32_bf16 v[64:67], v[248:251], v[48:51], v[12:15]
	v_mfma_f32_16x16x32_bf16 v[12:15], v[230:233], v[44:47], v[108:111]
	v_mfma_f32_16x16x32_bf16 v[60:63], v[194:197], v[48:51], v[12:15]
	v_mfma_f32_16x16x32_bf16 v[12:15], v[244:247], v[88:91], v[212:215]
	v_mfma_f32_16x16x32_bf16 v[48:51], v[248:251], v[92:95], v[12:15]
	v_mfma_f32_16x16x32_bf16 v[12:15], v[230:233], v[88:91], v[112:115]
	v_mfma_f32_16x16x32_bf16 v[44:47], v[194:197], v[92:95], v[12:15]
	v_mfma_f32_16x16x32_bf16 v[12:15], v[244:247], v[96:99], v[216:219]
	v_mfma_f32_16x16x32_bf16 v[32:35], v[248:251], v[100:103], v[12:15]
	v_mfma_f32_16x16x32_bf16 v[12:15], v[230:233], v[96:99], v[220:223]
	v_mfma_f32_16x16x32_bf16 v[28:31], v[194:197], v[100:103], v[12:15]
	v_mfma_f32_16x16x32_bf16 v[12:15], v[244:247], v[104:107], v[236:239]
	v_mfma_f32_16x16x32_bf16 v[16:19], v[248:251], v[188:191], v[12:15]
	v_mfma_f32_16x16x32_bf16 v[12:15], v[230:233], v[104:107], v[240:243]
	v_mfma_f32_16x16x32_bf16 v[12:15], v[194:197], v[188:191], v[12:15]
	s_barrier
	s_setprio 0
	s_lshl_b32 s28, s28, 11
	s_and_b32 s28, s28, 0x800
	s_add_i32 s60, s28, 0
	s_add_i32 s60, s60, 0x25a00
	s_lshl_b32 s28, s43, 2
	s_add_i32 s28, s60, s28
	s_add_u32 s26, s26, 0x40180
	s_addc_u32 s27, s27, 0
	v_mbcnt_lo_u32_b32 v88, -1, 0
	v_mbcnt_hi_u32_b32 v88, -1, v88
	s_add_u32 s61, s24, 0x200
	v_lshl_add_u32 v88, v88, 2, s28
	s_addc_u32 s62, s25, 0
	s_mov_b32 s76, 0
	s_waitcnt vmcnt(8)
	ds_write_b32 v88, v84

.LBB0_593:
	v_and_b32_e32 v21, 48, v12
	v_lshlrev_b32_e32 v12, 6, v12
	s_movk_i32 s10, 0x3c0
	s_and_b32 s1, s1, 3
	s_lshl_b32 s56, s3, 6
	s_lshl_b32 s3, s3, 13
	v_and_or_b32 v12, v12, s10, v21
	v_and_b32_e32 v2, 32, v2
	v_bitop3_b32 v21, v12, s3, v2 bitop3:0xde
	s_lshl_b32 s58, s1, 5
	s_lshl_b32 s3, s1, 12
	v_bitop3_b32 v204, s3, v12, v2 bitop3:0xf6
	s_add_u32 s3, s18, 0x100000
	s_addc_u32 s20, s19, 0
	s_add_u32 s10, s18, 0x12400000
	s_addc_u32 s11, s19, 0
	s_add_u32 s12, s18, 0x16500000
	s_addc_u32 s13, s19, 0
	s_add_u32 s14, s18, 0x1af00000
	s_addc_u32 s15, s19, 0
	s_add_u32 s21, s52, s35
	s_addc_u32 s22, s53, s36
	s_and_b64 s[16:17], s[6:7], exec
	s_cselect_b32 s17, s20, s22
	s_cselect_b32 s16, s3, s21
	s_add_u32 s3, s18, 0x101000
	s_addc_u32 s20, s19, 0
	s_add_u32 s21, s54, s35
	s_addc_u32 s22, s55, s36
	s_and_b64 s[18:19], s[6:7], exec
	s_cselect_b32 s19, s20, s22
	s_cselect_b32 s18, s3, s21
	s_add_i32 m0, s46, 0x18000
	v_lshl_add_u64 v[10:11], v[10:11], 0, s[74:75]
	s_waitcnt vmcnt(2)
	s_barrier
	global_load_lds_dwordx4 v[10:11], off
	v_lshl_add_u64 v[8:9], v[8:9], 0, s[74:75]
	s_add_i32 m0, s46, 0x1a000
	s_add_i32 s52, s46, 0x8000
	s_add_i32 s53, s46, 0xa000
	global_load_lds_dwordx4 v[8:9], off
	v_lshl_add_u64 v[4:5], v[4:5], 0, s[74:75]
	s_mov_b32 m0, s52
	s_add_u32 s20, s28, 0xb0080
	global_load_lds_dwordx4 v[4:5], off
	v_lshl_add_u64 v[4:5], v[6:7], 0, s[74:75]
	s_mov_b32 m0, s53
	s_addc_u32 s21, s29, 0
	global_load_lds_dwordx4 v[4:5], off
	s_add_i32 m0, s46, 0x1c000
	v_lshl_add_u64 v[4:5], s[20:21], 0, v[160:161]
	global_load_lds_dwordx4 v[4:5], off
	v_lshl_add_u64 v[4:5], s[20:21], 0, v[164:165]
	s_add_i32 m0, s46, 0x1e000
	s_movk_i32 s3, 0xb00
	global_load_lds_dwordx4 v[4:5], off
	s_cmpk_lt_u32 s0, 0x100
	v_lshrrev_b32_e32 v4, 1, v13
	v_mul_lo_u32 v2, v15, s3
	s_mov_b32 s22, 0xb000
	s_cselect_b64 s[20:21], -1, 0
	s_lshl_b32 s64, s1, 1
	v_mad_u64_u32 v[4:5], s[0:1], v4, s22, v[2:3]
	v_or_b32_e32 v2, v4, v14
	v_add_lshl_u32 v2, v2, v16, 1
	s_mov_b64 s[24:25], 0xb0180
	v_lshl_add_u64 v[166:167], v[2:3], 0, s[24:25]
	v_lshrrev_b32_e32 v4, 1, v17
	v_mul_lo_u32 v2, v19, s3
	v_mad_u64_u32 v[4:5], s[0:1], v4, s22, v[2:3]
	s_waitcnt vmcnt(0)
	v_or_b32_e32 v2, v4, v18
	v_add_lshl_u32 v2, v2, v20, 1
	v_lshl_add_u64 v[168:169], v[2:3], 0, s[24:25]
	s_mov_b32 s60, 0
	v_add_u32_e32 v205, 0, v21
	s_mov_b32 s54, 0
	s_barrier
	s_branch .LBB0_596

.LBB0_606:
	s_add_i32 s3, 0, 0x10000
	s_add_i32 s41, 0, 0x14000
	v_add_u32_e32 v2, s3, v204
	v_add_u32_e32 v112, s41, v204
	ds_read_b128 v[4:7], v2
	ds_read_b128 v[8:11], v2 offset:1024
	ds_read_b128 v[12:15], v2 offset:2048
	ds_read_b128 v[16:19], v2 offset:3072
	ds_read_b128 v[20:23], v112
	ds_read_b128 v[24:27], v112 offset:1024
	ds_read_b128 v[28:31], v112 offset:2048
	ds_read_b128 v[32:35], v112 offset:3072
	s_add_u32 s30, s26, 0xb0080
	s_addc_u32 s31, s27, 0
	s_add_i32 s0, s46, 0xc000
	v_lshl_add_u64 v[68:69], s[30:31], 0, v[0:1]
	s_mov_b32 m0, s0
	s_add_i32 s1, s46, 0xe000
	ds_read_b128 v[36:39], v205
	ds_read_b128 v[40:43], v205 offset:1024
	ds_read_b128 v[44:47], v205 offset:2048
	ds_read_b128 v[48:51], v205 offset:3072
	ds_read_b128 v[52:55], v205 offset:4096
	ds_read_b128 v[56:59], v205 offset:5120
	ds_read_b128 v[60:63], v205 offset:6144
	ds_read_b128 v[64:67], v205 offset:7168
	global_load_lds_dwordx4 v[68:69], off
	v_lshl_add_u64 v[68:69], s[30:31], 0, v[162:163]
	s_mov_b32 m0, s1
	s_nop 0
	global_load_lds_dwordx4 v[68:69], off
	s_waitcnt vmcnt(24)
	s_waitcnt lgkmcnt(0)
	s_setprio 1
	s_barrier
	v_mfma_f32_16x16x32_bf16 v[68:71], v[4:7], v[36:39], 0
	v_mfma_f32_16x16x32_bf16 v[72:75], v[12:15], v[36:39], 0
	v_mfma_f32_16x16x32_bf16 v[76:79], v[4:7], v[44:47], 0
	v_mfma_f32_16x16x32_bf16 v[80:83], v[12:15], v[44:47], 0
	v_mfma_f32_16x16x32_bf16 v[84:87], v[4:7], v[52:55], 0
	v_mfma_f32_16x16x32_bf16 v[88:91], v[12:15], v[52:55], 0
	v_mfma_f32_16x16x32_bf16 v[92:95], v[4:7], v[60:63], 0
	v_mfma_f32_16x16x32_bf16 v[96:99], v[12:15], v[60:63], 0
	v_mfma_f32_16x16x32_bf16 v[68:71], v[8:11], v[40:43], v[68:71]
	v_mfma_f32_16x16x32_bf16 v[72:75], v[16:19], v[40:43], v[72:75]
	v_mfma_f32_16x16x32_bf16 v[76:79], v[8:11], v[48:51], v[76:79]
	v_mfma_f32_16x16x32_bf16 v[80:83], v[16:19], v[48:51], v[80:83]
	v_mfma_f32_16x16x32_bf16 v[84:87], v[8:11], v[56:59], v[84:87]
	v_mfma_f32_16x16x32_bf16 v[88:91], v[16:19], v[56:59], v[88:91]
	v_mfma_f32_16x16x32_bf16 v[92:95], v[8:11], v[64:67], v[92:95]
	v_mfma_f32_16x16x32_bf16 v[96:99], v[16:19], v[64:67], v[96:99]
	v_mfma_f32_16x16x32_bf16 v[100:103], v[20:23], v[36:39], 0
	v_mfma_f32_16x16x32_bf16 v[36:39], v[28:31], v[36:39], 0
	v_mfma_f32_16x16x32_bf16 v[104:107], v[24:27], v[40:43], v[100:103]
	v_mfma_f32_16x16x32_bf16 v[36:39], v[32:35], v[40:43], v[36:39]
	v_mfma_f32_16x16x32_bf16 v[40:43], v[20:23], v[44:47], 0
	v_mfma_f32_16x16x32_bf16 v[44:47], v[28:31], v[44:47], 0
	v_mfma_f32_16x16x32_bf16 v[40:43], v[24:27], v[48:51], v[40:43]
	v_mfma_f32_16x16x32_bf16 v[44:47], v[32:35], v[48:51], v[44:47]
	v_mfma_f32_16x16x32_bf16 v[48:51], v[20:23], v[52:55], 0
	v_mfma_f32_16x16x32_bf16 v[52:55], v[28:31], v[52:55], 0
	v_mfma_f32_16x16x32_bf16 v[48:51], v[24:27], v[56:59], v[48:51]
	v_mfma_f32_16x16x32_bf16 v[108:111], v[32:35], v[56:59], v[52:55]
	v_mfma_f32_16x16x32_bf16 v[52:55], v[20:23], v[60:63], 0
	s_nop 0
	v_mfma_f32_16x16x32_bf16 v[120:123], v[24:27], v[64:67], v[52:55]
	v_mfma_f32_16x16x32_bf16 v[52:55], v[28:31], v[60:63], 0
	s_nop 0
	v_mfma_f32_16x16x32_bf16 v[132:135], v[32:35], v[64:67], v[52:55]
	s_barrier
	s_setprio 0
	s_add_i32 s3, s3, s37
	v_lshl_add_u64 v[190:191], s[28:29], 0, v[160:161]
	s_mov_b64 s[76:77], 0x100
	s_add_i32 s40, s3, 0x2000
	v_lshl_add_u64 v[118:119], v[190:191], 0, s[76:77]
	s_mov_b32 m0, s3
	v_lshl_add_u64 v[192:193], s[28:29], 0, v[164:165]
	s_add_u32 s30, s28, 0xb0100
	ds_read_b128 v[52:55], v205 offset:16384
	ds_read_b128 v[56:59], v205 offset:17408
	ds_read_b128 v[60:63], v205 offset:18432
	ds_read_b128 v[64:67], v205 offset:19456
	ds_read_b128 v[100:103], v205 offset:20480
	ds_read_b128 v[114:117], v205 offset:21504
	ds_read_b128 v[124:127], v205 offset:22528
	ds_read_b128 v[128:131], v205 offset:23552
	global_load_lds_dwordx4 v[118:119], off
	v_lshl_add_u64 v[118:119], v[192:193], 0, s[76:77]
	s_mov_b32 m0, s40
	s_addc_u32 s31, s29, 0
	s_add_i32 s41, s41, s37
	global_load_lds_dwordx4 v[118:119], off
	v_lshl_add_u64 v[118:119], s[30:31], 0, v[160:161]
	s_mov_b32 m0, s41
	s_add_i32 s61, s41, 0x2000
	global_load_lds_dwordx4 v[118:119], off
	v_lshl_add_u64 v[118:119], s[30:31], 0, v[164:165]
	s_mov_b32 m0, s61
	v_lshl_add_u64 v[198:199], s[26:27], 0, v[0:1]
	global_load_lds_dwordx4 v[118:119], off
	v_lshl_add_u64 v[118:119], v[198:199], 0, s[76:77]
	s_mov_b32 m0, s46
	v_lshl_add_u64 v[234:235], s[26:27], 0, v[162:163]
	global_load_lds_dwordx4 v[118:119], off
	v_lshl_add_u64 v[118:119], v[234:235], 0, s[76:77]
	s_mov_b32 m0, s48
	s_nop 0
	global_load_lds_dwordx4 v[118:119], off
	s_waitcnt vmcnt(24)
	s_waitcnt lgkmcnt(0)
	s_setprio 1
	s_barrier
	v_mfma_f32_16x16x32_bf16 v[136:139], v[4:7], v[52:55], 0
	s_nop 0
	v_mfma_f32_16x16x32_bf16 v[144:147], v[8:11], v[56:59], v[136:139]
	v_mfma_f32_16x16x32_bf16 v[136:139], v[12:15], v[52:55], 0
	s_nop 0
	v_mfma_f32_16x16x32_bf16 v[148:151], v[16:19], v[56:59], v[136:139]
	v_mfma_f32_16x16x32_bf16 v[136:139], v[4:7], v[60:63], 0
	s_nop 0
	v_mfma_f32_16x16x32_bf16 v[152:155], v[8:11], v[64:67], v[136:139]
	v_mfma_f32_16x16x32_bf16 v[136:139], v[12:15], v[60:63], 0
	s_nop 0
	v_mfma_f32_16x16x32_bf16 v[156:159], v[16:19], v[64:67], v[136:139]
	v_mfma_f32_16x16x32_bf16 v[136:139], v[4:7], v[100:103], 0
	v_mfma_f32_16x16x32_bf16 v[4:7], v[4:7], v[124:127], 0
	v_mfma_f32_16x16x32_bf16 v[170:173], v[8:11], v[114:117], v[136:139]
	v_mfma_f32_16x16x32_bf16 v[4:7], v[8:11], v[128:131], v[4:7]
	v_mfma_f32_16x16x32_bf16 v[8:11], v[12:15], v[124:127], 0
	s_nop 0
	v_mfma_f32_16x16x32_bf16 v[8:11], v[16:19], v[128:131], v[8:11]
	v_mfma_f32_16x16x32_bf16 v[136:139], v[12:15], v[100:103], 0
	s_nop 0
	v_mfma_f32_16x16x32_bf16 v[174:177], v[16:19], v[114:117], v[136:139]
	v_mfma_f32_16x16x32_bf16 v[12:15], v[20:23], v[52:55], 0
	v_mfma_f32_16x16x32_bf16 v[16:19], v[28:31], v[52:55], 0
	v_mfma_f32_16x16x32_bf16 v[52:55], v[20:23], v[60:63], 0
	s_nop 0
	v_mfma_f32_16x16x32_bf16 v[178:181], v[24:27], v[64:67], v[52:55]
	v_mfma_f32_16x16x32_bf16 v[52:55], v[28:31], v[60:63], 0
	v_mfma_f32_16x16x32_bf16 v[12:15], v[24:27], v[56:59], v[12:15]
	v_mfma_f32_16x16x32_bf16 v[16:19], v[32:35], v[56:59], v[16:19]
	v_mfma_f32_16x16x32_bf16 v[182:185], v[32:35], v[64:67], v[52:55]
	v_mfma_f32_16x16x32_bf16 v[52:55], v[20:23], v[100:103], 0
	v_mfma_f32_16x16x32_bf16 v[20:23], v[20:23], v[124:127], 0
	v_mfma_f32_16x16x32_bf16 v[186:189], v[24:27], v[114:117], v[52:55]
	v_mfma_f32_16x16x32_bf16 v[52:55], v[28:31], v[100:103], 0
	v_mfma_f32_16x16x32_bf16 v[200:203], v[24:27], v[128:131], v[20:23]
	v_mfma_f32_16x16x32_bf16 v[20:23], v[28:31], v[124:127], 0
	v_mfma_f32_16x16x32_bf16 v[194:197], v[32:35], v[114:117], v[52:55]
	v_mfma_f32_16x16x32_bf16 v[206:209], v[32:35], v[128:131], v[20:23]
	s_barrier
	s_setprio 0
	s_add_i32 s62, 0, 0x18000
	s_add_i32 s77, 0, 0x1c000
	v_add_u32_e32 v113, s62, v204
	v_add_u32_e32 v114, s77, v204
	ds_read_b128 v[20:23], v113
	ds_read_b128 v[24:27], v113 offset:1024
	ds_read_b128 v[28:31], v113 offset:2048
	ds_read_b128 v[32:35], v113 offset:3072
	ds_read_b128 v[210:213], v114
	ds_read_b128 v[214:217], v114 offset:1024
	ds_read_b128 v[218:221], v114 offset:2048
	ds_read_b128 v[222:225], v114 offset:3072
	s_add_u32 s30, s26, 0xb0100
	s_addc_u32 s31, s27, 0
	s_mov_b32 m0, s49
	v_lshl_add_u64 v[60:61], s[30:31], 0, v[0:1]
	ds_read_b128 v[52:55], v205 offset:32768
	ds_read_b128 v[56:59], v205 offset:33792
	ds_read_b128 v[230:233], v205 offset:34816
	ds_read_b128 v[236:239], v205 offset:35840
	ds_read_b128 v[240:243], v205 offset:36864
	ds_read_b128 v[244:247], v205 offset:37888
	ds_read_b128 v[248:251], v205 offset:38912
	ds_read_b128 v[226:229], v205 offset:39936
	global_load_lds_dwordx4 v[60:61], off
	v_lshl_add_u64 v[60:61], s[30:31], 0, v[162:163]
	s_mov_b32 m0, s50
	s_nop 0
	global_load_lds_dwordx4 v[60:61], off
	s_waitcnt vmcnt(8)
	s_waitcnt lgkmcnt(0)
	s_setprio 1
	s_barrier
	v_mfma_f32_16x16x32_bf16 v[60:63], v[20:23], v[52:55], v[68:71]
	v_mfma_f32_16x16x32_bf16 v[140:143], v[24:27], v[56:59], v[60:63]
	v_mfma_f32_16x16x32_bf16 v[60:63], v[28:31], v[52:55], v[72:75]
	v_mfma_f32_16x16x32_bf16 v[136:139], v[32:35], v[56:59], v[60:63]
	v_mfma_f32_16x16x32_bf16 v[60:63], v[20:23], v[230:233], v[76:79]
	v_mfma_f32_16x16x32_bf16 v[128:131], v[24:27], v[236:239], v[60:63]
	v_mfma_f32_16x16x32_bf16 v[60:63], v[28:31], v[230:233], v[80:83]
	v_mfma_f32_16x16x32_bf16 v[124:127], v[32:35], v[236:239], v[60:63]
	v_mfma_f32_16x16x32_bf16 v[60:63], v[20:23], v[240:243], v[84:87]
	v_mfma_f32_16x16x32_bf16 v[116:119], v[24:27], v[244:247], v[60:63]
	v_mfma_f32_16x16x32_bf16 v[60:63], v[28:31], v[240:243], v[88:91]
	v_mfma_f32_16x16x32_bf16 v[100:103], v[32:35], v[244:247], v[60:63]
	v_mfma_f32_16x16x32_bf16 v[60:63], v[20:23], v[248:251], v[92:95]
	v_mfma_f32_16x16x32_bf16 v[88:91], v[24:27], v[226:229], v[60:63]
	v_mfma_f32_16x16x32_bf16 v[60:63], v[28:31], v[248:251], v[96:99]
	v_mfma_f32_16x16x32_bf16 v[76:79], v[32:35], v[226:229], v[60:63]
	v_mfma_f32_16x16x32_bf16 v[60:63], v[210:213], v[52:55], v[104:107]
	v_mfma_f32_16x16x32_bf16 v[36:39], v[218:221], v[52:55], v[36:39]
	v_mfma_f32_16x16x32_bf16 v[64:67], v[214:217], v[56:59], v[60:63]
	v_mfma_f32_16x16x32_bf16 v[60:63], v[222:225], v[56:59], v[36:39]
	v_mfma_f32_16x16x32_bf16 v[36:39], v[210:213], v[230:233], v[40:43]
	v_mfma_f32_16x16x32_bf16 v[56:59], v[214:217], v[236:239], v[36:39]
	v_mfma_f32_16x16x32_bf16 v[36:39], v[218:221], v[230:233], v[44:47]
	v_mfma_f32_16x16x32_bf16 v[52:55], v[222:225], v[236:239], v[36:39]
	v_mfma_f32_16x16x32_bf16 v[36:39], v[210:213], v[240:243], v[48:51]
	v_mfma_f32_16x16x32_bf16 v[48:51], v[214:217], v[244:247], v[36:39]
	v_mfma_f32_16x16x32_bf16 v[36:39], v[218:221], v[240:243], v[108:111]
	v_mfma_f32_16x16x32_bf16 v[44:47], v[222:225], v[244:247], v[36:39]
	v_mfma_f32_16x16x32_bf16 v[36:39], v[210:213], v[248:251], v[120:123]
	v_mfma_f32_16x16x32_bf16 v[40:43], v[214:217], v[226:229], v[36:39]
	v_mfma_f32_16x16x32_bf16 v[36:39], v[218:221], v[248:251], v[132:135]
	v_mfma_f32_16x16x32_bf16 v[36:39], v[222:225], v[226:229], v[36:39]
	s_barrier
	s_setprio 0
	s_add_i32 s62, s62, s37
	s_add_i32 s76, s62, 0x2000
	v_lshl_add_u64 v[68:69], v[190:191], 0, s[84:85]
	s_mov_b32 m0, s62
	s_add_u32 s30, s28, 0xb0180
	ds_read_b128 v[120:123], v205 offset:49152
	ds_read_b128 v[132:135], v205 offset:50176
	ds_read_b128 v[226:229], v205 offset:51200
	ds_read_b128 v[230:233], v205 offset:52224
	ds_read_b128 v[236:239], v205 offset:53248
	ds_read_b128 v[240:243], v205 offset:54272
	ds_read_b128 v[244:247], v205 offset:55296
	ds_read_b128 v[248:251], v205 offset:56320
	global_load_lds_dwordx4 v[68:69], off
	v_lshl_add_u64 v[68:69], v[192:193], 0, s[84:85]
	s_mov_b32 m0, s76
	s_addc_u32 s31, s29, 0
	s_add_i32 s77, s77, s37
	global_load_lds_dwordx4 v[68:69], off
	v_lshl_add_u64 v[68:69], s[30:31], 0, v[160:161]
	s_mov_b32 m0, s77
	s_add_i32 s79, s77, 0x2000
	global_load_lds_dwordx4 v[68:69], off
	v_lshl_add_u64 v[68:69], s[30:31], 0, v[164:165]
	s_mov_b32 m0, s79
	s_nop 0
	global_load_lds_dwordx4 v[68:69], off
	v_lshl_add_u64 v[68:69], v[198:199], 0, s[84:85]
	s_mov_b32 m0, s52
	s_nop 0
	global_load_lds_dwordx4 v[68:69], off
	v_lshl_add_u64 v[68:69], v[234:235], 0, s[84:85]
	s_mov_b32 m0, s53
	s_nop 0
	global_load_lds_dwordx4 v[68:69], off
	s_waitcnt vmcnt(8)
	s_waitcnt lgkmcnt(0)
	s_setprio 1
	s_barrier
	v_mfma_f32_16x16x32_bf16 v[68:71], v[20:23], v[120:123], v[144:147]
	v_mfma_f32_16x16x32_bf16 v[108:111], v[24:27], v[132:135], v[68:71]
	v_mfma_f32_16x16x32_bf16 v[68:71], v[28:31], v[120:123], v[148:151]
	v_mfma_f32_16x16x32_bf16 v[104:107], v[32:35], v[132:135], v[68:71]
	v_mfma_f32_16x16x32_bf16 v[68:71], v[20:23], v[226:229], v[152:155]
	v_mfma_f32_16x16x32_bf16 v[96:99], v[24:27], v[230:233], v[68:71]
	v_mfma_f32_16x16x32_bf16 v[68:71], v[28:31], v[226:229], v[156:159]
	v_mfma_f32_16x16x32_bf16 v[92:95], v[32:35], v[230:233], v[68:71]
	v_mfma_f32_16x16x32_bf16 v[68:71], v[20:23], v[236:239], v[170:173]
	v_mfma_f32_16x16x32_bf16 v[4:7], v[20:23], v[244:247], v[4:7]
	v_mfma_f32_16x16x32_bf16 v[84:87], v[24:27], v[240:243], v[68:71]
	v_mfma_f32_16x16x32_bf16 v[68:71], v[28:31], v[236:239], v[174:177]
	v_mfma_f32_16x16x32_bf16 v[72:75], v[24:27], v[248:251], v[4:7]
	v_mfma_f32_16x16x32_bf16 v[4:7], v[28:31], v[244:247], v[8:11]
	v_mfma_f32_16x16x32_bf16 v[80:83], v[32:35], v[240:243], v[68:71]
	v_mfma_f32_16x16x32_bf16 v[68:71], v[32:35], v[248:251], v[4:7]
	v_mfma_f32_16x16x32_bf16 v[4:7], v[210:213], v[120:123], v[12:15]
	v_mfma_f32_16x16x32_bf16 v[32:35], v[214:217], v[132:135], v[4:7]
	v_mfma_f32_16x16x32_bf16 v[4:7], v[218:221], v[120:123], v[16:19]
	v_mfma_f32_16x16x32_bf16 v[28:31], v[222:225], v[132:135], v[4:7]
	v_mfma_f32_16x16x32_bf16 v[4:7], v[210:213], v[226:229], v[178:181]
	v_mfma_f32_16x16x32_bf16 v[24:27], v[214:217], v[230:233], v[4:7]
	v_mfma_f32_16x16x32_bf16 v[4:7], v[218:221], v[226:229], v[182:185]
	v_mfma_f32_16x16x32_bf16 v[20:23], v[222:225], v[230:233], v[4:7]
	v_mfma_f32_16x16x32_bf16 v[4:7], v[210:213], v[236:239], v[186:189]
	v_mfma_f32_16x16x32_bf16 v[16:19], v[214:217], v[240:243], v[4:7]
	v_mfma_f32_16x16x32_bf16 v[4:7], v[218:221], v[236:239], v[194:197]
	v_mfma_f32_16x16x32_bf16 v[12:15], v[222:225], v[240:243], v[4:7]
	v_mfma_f32_16x16x32_bf16 v[4:7], v[210:213], v[244:247], v[200:203]
	v_mfma_f32_16x16x32_bf16 v[8:11], v[214:217], v[248:251], v[4:7]
	v_mfma_f32_16x16x32_bf16 v[4:7], v[218:221], v[244:247], v[206:209]
	v_mfma_f32_16x16x32_bf16 v[4:7], v[222:225], v[248:251], v[4:7]
	s_barrier
	s_setprio 0
	s_add_u32 s80, s28, 0x200
	s_addc_u32 s88, s29, 0
	s_mov_b32 s90, 0

.LBB0_945:
	s_lshl_b64 s[16:17], s[64:65], 27
	s_add_u32 s1, s54, 0x1b800000
	s_addc_u32 s3, s55, 0
	s_add_u32 s4, s52, s16
	s_addc_u32 s5, s53, s17
	s_add_u32 s61, s4, 0x8200000
	s_addc_u32 s80, s5, 0
	s_add_u32 s4, s52, s6
	s_addc_u32 s5, s53, s7
	s_add_u32 s52, s4, 0x28678000
	s_addc_u32 s53, s5, 0
	s_lshl_b64 s[16:17], s[10:11], 2
	s_add_u32 s4, s54, s16
	s_addc_u32 s5, s55, s17
	s_add_u32 s16, s4, 0x15a000
	s_addc_u32 s17, s5, 0
	s_add_u32 s18, s4, 0x15d000
	s_addc_u32 s19, s5, 0
	v_and_b32_e32 v4, 48, v10
	v_lshlrev_b32_e32 v5, 6, v10
	s_movk_i32 s5, 0x3c0
	s_lshl_b32 s4, s13, 13
	v_and_or_b32 v4, v5, s5, v4
	v_and_b32_e32 v2, 32, v2
	v_bitop3_b32 v5, v4, s4, v2 bitop3:0xde
	s_lshl_b32 s4, s20, 5
	s_and_b32 s55, s4, 0x60
	s_lshl_b32 s4, s55, 7
	v_bitop3_b32 v184, s4, v4, v2 bitop3:0xf6
	v_lshlrev_b32_e32 v2, 14, v11
	v_and_b32_e32 v2, 0xffff8000, v2
	v_lshl_add_u32 v2, v12, 11, v2
	v_and_b32_e32 v4, 1, v11
	v_lshl_or_b32 v2, v4, 6, v2
	v_lshl_add_u32 v170, v13, 1, v2
	v_lshlrev_b32_e32 v2, 14, v14
	v_and_b32_e32 v2, 0xffff8000, v2
	s_lshl_b32 s54, s13, 6
	s_waitcnt vmcnt(0)
	v_lshl_add_u32 v2, v15, 11, v2
	v_and_b32_e32 v4, 1, v14
	s_cmpk_lt_u32 s0, 0x100
	v_lshl_or_b32 v2, v4, 6, v2
	s_cselect_b64 s[20:21], -1, 0
	v_mov_b32_e32 v171, v3
	v_lshl_add_u32 v172, v16, 1, v2
	v_mov_b32_e32 v173, v3
	s_mov_b32 s13, 0
	v_add_u32_e32 v185, 0, v5
	s_mov_b32 s88, 0
	s_barrier
	s_branch .LBB0_948

.LBB0_950:
	s_ashr_i32 s25, s24, 31
	s_lshl_b64 s[26:27], s[24:25], 19
	s_add_u32 s0, s49, s26
	s_addc_u32 s4, s50, s27
	s_ashr_i32 s23, s22, 31
	s_lshl_b64 s[26:27], s[22:23], 19
	s_add_u32 s5, s51, s26
	s_addc_u32 s23, s56, s27
	s_add_i32 s25, 0, 0x10000
	s_and_b64 s[26:27], s[38:39], exec
	s_cselect_b32 s27, s4, s37
	s_cselect_b32 s26, s0, s36
	s_add_i32 s42, 0, 0x14000
	v_add_u32_e32 v2, s25, v184
	v_add_u32_e32 v52, s42, v184
	ds_read_b128 v[4:7], v2
	ds_read_b128 v[8:11], v2 offset:1024
	ds_read_b128 v[12:15], v2 offset:2048
	ds_read_b128 v[16:19], v2 offset:3072
	ds_read_b128 v[20:23], v52
	ds_read_b128 v[24:27], v52 offset:1024
	ds_read_b128 v[28:31], v52 offset:2048
	ds_read_b128 v[32:35], v52 offset:3072
	s_and_b64 s[28:29], s[38:39], exec
	s_cselect_b32 s29, s23, s35
	s_cselect_b32 s28, s5, s34
	s_add_u32 s40, s36, 0x40080
	s_addc_u32 s41, s37, 0
	s_add_i32 s0, s58, 0xc000
	v_lshl_add_u64 v[70:71], s[40:41], 0, v[0:1]
	s_mov_b32 m0, s0
	s_add_i32 s23, s58, 0xe000
	ds_read_b128 v[36:39], v185
	ds_read_b128 v[40:43], v185 offset:1024
	ds_read_b128 v[44:47], v185 offset:2048
	ds_read_b128 v[48:51], v185 offset:3072
	ds_read_b128 v[54:57], v185 offset:4096
	ds_read_b128 v[58:61], v185 offset:5120
	ds_read_b128 v[62:65], v185 offset:6144
	ds_read_b128 v[66:69], v185 offset:7168
	global_load_lds_dwordx4 v[70:71], off
	v_lshl_add_u64 v[70:71], s[40:41], 0, v[166:167]
	s_mov_b32 m0, s23
	s_nop 0
	global_load_lds_dwordx4 v[70:71], off
	s_waitcnt vmcnt(24)
	s_waitcnt lgkmcnt(0)
	s_setprio 1
	s_barrier
	v_mfma_f32_16x16x32_f16 v[94:97], v[4:7], v[62:65], 0
	v_mfma_f32_16x16x32_f16 v[98:101], v[12:15], v[62:65], 0
	v_mfma_f32_16x16x32_f16 v[70:73], v[4:7], v[36:39], 0
	v_mfma_f32_16x16x32_f16 v[74:77], v[12:15], v[36:39], 0
	v_mfma_f32_16x16x32_f16 v[78:81], v[4:7], v[44:47], 0
	v_mfma_f32_16x16x32_f16 v[82:85], v[12:15], v[44:47], 0
	v_mfma_f32_16x16x32_f16 v[90:93], v[12:15], v[54:57], 0
	v_mfma_f32_16x16x32_f16 v[156:159], v[8:11], v[40:43], v[70:73]
	v_mfma_f32_16x16x32_f16 v[142:145], v[16:19], v[40:43], v[74:77]
	v_mfma_f32_16x16x32_f16 v[152:155], v[8:11], v[48:51], v[78:81]
	v_mfma_f32_16x16x32_f16 v[138:141], v[16:19], v[48:51], v[82:85]
	v_mfma_f32_16x16x32_f16 v[148:151], v[16:19], v[58:61], v[90:93]
	v_mfma_f32_16x16x32_f16 v[94:97], v[8:11], v[66:69], v[94:97]
	v_mfma_f32_16x16x32_f16 v[98:101], v[16:19], v[66:69], v[98:101]
	v_mfma_f32_16x16x32_f16 v[86:89], v[4:7], v[54:57], 0
	s_nop 0
	v_mfma_f32_16x16x32_f16 v[84:87], v[8:11], v[58:61], v[86:89]
	v_mfma_f32_16x16x32_f16 v[102:105], v[20:23], v[36:39], 0
	v_mfma_f32_16x16x32_f16 v[36:39], v[28:31], v[36:39], 0
	v_mfma_f32_16x16x32_f16 v[102:105], v[24:27], v[40:43], v[102:105]
	v_mfma_f32_16x16x32_f16 v[88:91], v[32:35], v[40:43], v[36:39]
	v_mfma_f32_16x16x32_f16 v[40:43], v[20:23], v[44:47], 0
	v_mfma_f32_16x16x32_f16 v[44:47], v[28:31], v[44:47], 0
	v_mfma_f32_16x16x32_f16 v[40:43], v[24:27], v[48:51], v[40:43]
	v_mfma_f32_16x16x32_f16 v[36:39], v[32:35], v[48:51], v[44:47]
	v_mfma_f32_16x16x32_f16 v[48:51], v[20:23], v[54:57], 0
	s_nop 0
	v_mfma_f32_16x16x32_f16 v[48:51], v[24:27], v[58:61], v[48:51]
	v_mfma_f32_16x16x32_f16 v[54:57], v[28:31], v[54:57], 0
	s_nop 0
	v_mfma_f32_16x16x32_f16 v[56:59], v[32:35], v[58:61], v[54:57]
	v_mfma_f32_16x16x32_f16 v[106:109], v[20:23], v[62:65], 0
	v_mfma_f32_16x16x32_f16 v[60:63], v[28:31], v[62:65], 0
	v_mfma_f32_16x16x32_f16 v[174:177], v[24:27], v[66:69], v[106:109]
	v_mfma_f32_16x16x32_f16 v[60:63], v[32:35], v[66:69], v[60:63]
	s_barrier
	s_setprio 0
	s_add_i32 s25, s25, s57
	v_lshl_add_u64 v[182:183], s[34:35], 0, v[164:165]
	s_mov_b64 s[4:5], 0x100
	s_add_i32 s31, s25, 0x2000
	v_lshl_add_u64 v[54:55], v[182:183], 0, s[4:5]
	s_mov_b32 m0, s25
	v_lshl_add_u64 v[198:199], s[34:35], 0, v[168:169]
	s_add_u32 s40, s34, 0x40100
	ds_read_b128 v[64:67], v185 offset:16384
	ds_read_b128 v[106:109], v185 offset:17408
	ds_read_b128 v[110:113], v185 offset:18432
	ds_read_b128 v[114:117], v185 offset:19456
	ds_read_b128 v[118:121], v185 offset:20480
	ds_read_b128 v[122:125], v185 offset:21504
	ds_read_b128 v[126:129], v185 offset:22528
	ds_read_b128 v[130:133], v185 offset:23552
	global_load_lds_dwordx4 v[54:55], off
	v_lshl_add_u64 v[54:55], v[198:199], 0, s[4:5]
	s_mov_b32 m0, s31
	s_addc_u32 s41, s35, 0
	s_add_i32 s42, s42, s57
	global_load_lds_dwordx4 v[54:55], off
	v_lshl_add_u64 v[54:55], s[40:41], 0, v[164:165]
	s_mov_b32 m0, s42
	s_add_i32 s43, s42, 0x2000
	global_load_lds_dwordx4 v[54:55], off
	v_lshl_add_u64 v[54:55], s[40:41], 0, v[168:169]
	s_mov_b32 m0, s43
	v_lshl_add_u64 v[252:253], s[36:37], 0, v[0:1]
	global_load_lds_dwordx4 v[54:55], off
	v_lshl_add_u64 v[54:55], v[252:253], 0, s[4:5]
	s_mov_b32 m0, s58
	v_lshl_add_u64 v[44:45], s[36:37], 0, v[166:167]
	global_load_lds_dwordx4 v[54:55], off
	v_lshl_add_u64 v[46:47], v[44:45], 0, s[4:5]
	s_mov_b32 m0, s59
	s_nop 0
	global_load_lds_dwordx4 v[46:47], off
	s_waitcnt vmcnt(24)
	s_waitcnt lgkmcnt(0)
	s_setprio 1
	s_barrier
	v_mfma_f32_16x16x32_f16 v[134:137], v[4:7], v[64:67], 0
	s_nop 0
	v_mfma_f32_16x16x32_f16 v[178:181], v[8:11], v[106:109], v[134:137]
	v_mfma_f32_16x16x32_f16 v[134:137], v[12:15], v[64:67], 0
	s_nop 0
	v_mfma_f32_16x16x32_f16 v[186:189], v[16:19], v[106:109], v[134:137]
	v_mfma_f32_16x16x32_f16 v[134:137], v[4:7], v[110:113], 0
	s_nop 0
	v_mfma_f32_16x16x32_f16 v[194:197], v[8:11], v[114:117], v[134:137]
	v_mfma_f32_16x16x32_f16 v[134:137], v[12:15], v[110:113], 0
	s_nop 0
	v_mfma_f32_16x16x32_f16 v[200:203], v[16:19], v[114:117], v[134:137]
	v_mfma_f32_16x16x32_f16 v[134:137], v[4:7], v[118:121], 0
	v_mfma_f32_16x16x32_f16 v[4:7], v[4:7], v[126:129], 0
	v_mfma_f32_16x16x32_f16 v[204:207], v[8:11], v[122:125], v[134:137]
	v_mfma_f32_16x16x32_f16 v[4:7], v[8:11], v[130:133], v[4:7]
	v_mfma_f32_16x16x32_f16 v[8:11], v[12:15], v[126:129], 0
	s_nop 0
	v_mfma_f32_16x16x32_f16 v[8:11], v[16:19], v[130:133], v[8:11]
	v_mfma_f32_16x16x32_f16 v[134:137], v[12:15], v[118:121], 0
	s_nop 0
	v_mfma_f32_16x16x32_f16 v[208:211], v[16:19], v[122:125], v[134:137]
	v_mfma_f32_16x16x32_f16 v[12:15], v[20:23], v[64:67], 0
	s_nop 0
	v_mfma_f32_16x16x32_f16 v[212:215], v[24:27], v[106:109], v[12:15]
	v_mfma_f32_16x16x32_f16 v[12:15], v[28:31], v[64:67], 0
	s_nop 0
	v_mfma_f32_16x16x32_f16 v[64:67], v[32:35], v[106:109], v[12:15]
	v_mfma_f32_16x16x32_f16 v[12:15], v[20:23], v[110:113], 0
	s_nop 0
	v_mfma_f32_16x16x32_f16 v[216:219], v[24:27], v[114:117], v[12:15]
	v_mfma_f32_16x16x32_f16 v[12:15], v[28:31], v[110:113], 0
	s_nop 0
	v_mfma_f32_16x16x32_f16 v[220:223], v[32:35], v[114:117], v[12:15]
	v_mfma_f32_16x16x32_f16 v[12:15], v[20:23], v[118:121], 0
	s_nop 0
	v_mfma_f32_16x16x32_f16 v[224:227], v[24:27], v[122:125], v[12:15]
	v_mfma_f32_16x16x32_f16 v[12:15], v[28:31], v[118:121], 0
	s_nop 0
	v_mfma_f32_16x16x32_f16 v[228:231], v[32:35], v[122:125], v[12:15]
	v_mfma_f32_16x16x32_f16 v[12:15], v[20:23], v[126:129], 0
	s_nop 0
	v_mfma_f32_16x16x32_f16 v[236:239], v[24:27], v[130:133], v[12:15]
	v_mfma_f32_16x16x32_f16 v[12:15], v[28:31], v[126:129], 0
	s_nop 0
	v_mfma_f32_16x16x32_f16 v[240:243], v[32:35], v[130:133], v[12:15]
	s_barrier
	s_setprio 0
	s_add_i32 s44, 0, 0x18000
	s_add_i32 s90, 0, 0x1c000
	v_add_u32_e32 v53, s44, v184
	v_add_u32_e32 v54, s90, v184
	ds_read_b128 v[12:15], v53
	ds_read_b128 v[16:19], v53 offset:1024
	ds_read_b128 v[20:23], v53 offset:2048
	ds_read_b128 v[24:27], v53 offset:3072
	ds_read_b128 v[244:247], v54
	ds_read_b128 v[248:251], v54 offset:1024
	ds_read_b128 v[190:193], v54 offset:2048
	ds_read_b128 v[232:235], v54 offset:3072
	s_add_u32 s40, s36, 0x40100
	s_addc_u32 s41, s37, 0
	s_mov_b32 m0, s60
	v_lshl_add_u64 v[46:47], s[40:41], 0, v[0:1]
	ds_read_b128 v[28:31], v185 offset:32768
	ds_read_b128 v[32:35], v185 offset:33792
	ds_read_b128 v[116:119], v185 offset:34816
	ds_read_b128 v[120:123], v185 offset:35840
	ds_read_b128 v[68:71], v185 offset:36864
	ds_read_b128 v[72:75], v185 offset:37888
	ds_read_b128 v[76:79], v185 offset:38912
	ds_read_b128 v[80:83], v185 offset:39936
	global_load_lds_dwordx4 v[46:47], off
	v_lshl_add_u64 v[46:47], s[40:41], 0, v[166:167]
	s_mov_b32 m0, s62
	s_nop 0
	global_load_lds_dwordx4 v[46:47], off
	s_waitcnt vmcnt(8)
	s_waitcnt lgkmcnt(0)
	s_setprio 1
	s_barrier
	v_mfma_f32_16x16x32_f16 v[106:109], v[12:15], v[28:31], v[156:159]
	v_mfma_f32_16x16x32_f16 v[84:87], v[12:15], v[68:71], v[84:87]
	v_mfma_f32_16x16x32_f16 v[160:163], v[16:19], v[32:35], v[106:109]
	v_mfma_f32_16x16x32_f16 v[106:109], v[20:23], v[28:31], v[142:145]
	v_mfma_f32_16x16x32_f16 v[128:131], v[16:19], v[72:75], v[84:87]
	v_mfma_f32_16x16x32_f16 v[84:87], v[20:23], v[68:71], v[148:151]
	v_mfma_f32_16x16x32_f16 v[156:159], v[24:27], v[32:35], v[106:109]
	v_mfma_f32_16x16x32_f16 v[106:109], v[12:15], v[116:119], v[152:155]
	v_mfma_f32_16x16x32_f16 v[124:127], v[24:27], v[72:75], v[84:87]
	v_mfma_f32_16x16x32_f16 v[84:87], v[12:15], v[76:79], v[94:97]
	v_mfma_f32_16x16x32_f16 v[144:147], v[16:19], v[120:123], v[106:109]
	v_mfma_f32_16x16x32_f16 v[106:109], v[20:23], v[116:119], v[138:141]
	v_mfma_f32_16x16x32_f16 v[112:115], v[16:19], v[80:83], v[84:87]
	v_mfma_f32_16x16x32_f16 v[84:87], v[20:23], v[76:79], v[98:101]
	v_mfma_f32_16x16x32_f16 v[140:143], v[24:27], v[120:123], v[106:109]
	v_mfma_f32_16x16x32_f16 v[108:111], v[24:27], v[80:83], v[84:87]
	v_mfma_f32_16x16x32_f16 v[84:87], v[244:247], v[28:31], v[102:105]
	v_mfma_f32_16x16x32_f16 v[28:31], v[190:193], v[28:31], v[88:91]
	v_mfma_f32_16x16x32_f16 v[148:151], v[232:235], v[32:35], v[28:31]
	v_mfma_f32_16x16x32_f16 v[28:31], v[244:247], v[116:119], v[40:43]
	v_mfma_f32_16x16x32_f16 v[136:139], v[248:251], v[120:123], v[28:31]
	v_mfma_f32_16x16x32_f16 v[28:31], v[190:193], v[116:119], v[36:39]
	v_mfma_f32_16x16x32_f16 v[132:135], v[232:235], v[120:123], v[28:31]
	v_mfma_f32_16x16x32_f16 v[28:31], v[244:247], v[68:71], v[48:51]
	v_mfma_f32_16x16x32_f16 v[120:123], v[248:251], v[72:75], v[28:31]
	v_mfma_f32_16x16x32_f16 v[28:31], v[190:193], v[68:71], v[56:59]
	v_mfma_f32_16x16x32_f16 v[116:119], v[232:235], v[72:75], v[28:31]
	v_mfma_f32_16x16x32_f16 v[28:31], v[244:247], v[76:79], v[174:177]
	v_mfma_f32_16x16x32_f16 v[104:107], v[248:251], v[80:83], v[28:31]
	v_mfma_f32_16x16x32_f16 v[28:31], v[190:193], v[76:79], v[60:63]
	v_mfma_f32_16x16x32_f16 v[152:155], v[248:251], v[32:35], v[84:87]
	v_mfma_f32_16x16x32_f16 v[100:103], v[232:235], v[80:83], v[28:31]
	s_barrier
	s_setprio 0
	s_add_i32 s44, s44, s57
	s_add_i32 s45, s44, 0x2000
	s_nop 1
	v_lshl_add_u64 v[28:29], v[182:183], 0, s[84:85]
	s_mov_b32 m0, s44
	s_add_u32 s40, s34, 0x40180
	ds_read_b128 v[36:39], v185 offset:49152
	ds_read_b128 v[40:43], v185 offset:50176
	ds_read_b128 v[56:59], v185 offset:51200
	ds_read_b128 v[60:63], v185 offset:52224
	ds_read_b128 v[68:71], v185 offset:53248
	ds_read_b128 v[76:79], v185 offset:54272
	ds_read_b128 v[84:87], v185 offset:55296
	ds_read_b128 v[88:91], v185 offset:56320
	global_load_lds_dwordx4 v[28:29], off
	v_lshl_add_u64 v[28:29], v[198:199], 0, s[84:85]
	s_mov_b32 m0, s45
	s_addc_u32 s41, s35, 0
	s_add_i32 s90, s90, s57
	global_load_lds_dwordx4 v[28:29], off
	v_lshl_add_u64 v[28:29], s[40:41], 0, v[164:165]
	s_mov_b32 m0, s90
	s_add_i32 s91, s90, 0x2000
	global_load_lds_dwordx4 v[28:29], off
	v_lshl_add_u64 v[28:29], s[40:41], 0, v[168:169]
	s_mov_b32 m0, s91
	s_nop 0
	global_load_lds_dwordx4 v[28:29], off
	v_lshl_add_u64 v[28:29], v[252:253], 0, s[84:85]
	s_mov_b32 m0, s76
	s_nop 0
	global_load_lds_dwordx4 v[28:29], off
	v_lshl_add_u64 v[28:29], v[44:45], 0, s[84:85]
	s_mov_b32 m0, s77
	s_nop 0
	global_load_lds_dwordx4 v[28:29], off
	s_waitcnt vmcnt(8)
	s_waitcnt lgkmcnt(0)
	s_setprio 1
	s_barrier
	v_mfma_f32_16x16x32_f16 v[28:31], v[12:15], v[36:39], v[178:181]
	v_mfma_f32_16x16x32_f16 v[96:99], v[16:19], v[40:43], v[28:31]
	v_mfma_f32_16x16x32_f16 v[28:31], v[20:23], v[36:39], v[186:189]
	v_mfma_f32_16x16x32_f16 v[92:95], v[24:27], v[40:43], v[28:31]
	v_mfma_f32_16x16x32_f16 v[28:31], v[12:15], v[56:59], v[194:197]
	v_mfma_f32_16x16x32_f16 v[48:51], v[16:19], v[60:63], v[28:31]
	v_mfma_f32_16x16x32_f16 v[28:31], v[20:23], v[56:59], v[200:203]
	v_mfma_f32_16x16x32_f16 v[44:47], v[24:27], v[60:63], v[28:31]
	v_mfma_f32_16x16x32_f16 v[28:31], v[12:15], v[68:71], v[204:207]
	v_mfma_f32_16x16x32_f16 v[4:7], v[12:15], v[84:87], v[4:7]
	v_mfma_f32_16x16x32_f16 v[32:35], v[16:19], v[76:79], v[28:31]
	v_mfma_f32_16x16x32_f16 v[28:31], v[20:23], v[68:71], v[208:211]
	v_mfma_f32_16x16x32_f16 v[16:19], v[16:19], v[88:91], v[4:7]
	v_mfma_f32_16x16x32_f16 v[4:7], v[20:23], v[84:87], v[8:11]
	v_mfma_f32_16x16x32_f16 v[28:31], v[24:27], v[76:79], v[28:31]
	v_mfma_f32_16x16x32_f16 v[12:15], v[24:27], v[88:91], v[4:7]
	v_mfma_f32_16x16x32_f16 v[4:7], v[244:247], v[36:39], v[212:215]
	v_mfma_f32_16x16x32_f16 v[80:83], v[248:251], v[40:43], v[4:7]
	v_mfma_f32_16x16x32_f16 v[4:7], v[190:193], v[36:39], v[64:67]
	v_mfma_f32_16x16x32_f16 v[72:75], v[232:235], v[40:43], v[4:7]
	v_mfma_f32_16x16x32_f16 v[4:7], v[244:247], v[56:59], v[216:219]
	v_mfma_f32_16x16x32_f16 v[40:43], v[248:251], v[60:63], v[4:7]
	v_mfma_f32_16x16x32_f16 v[4:7], v[190:193], v[56:59], v[220:223]
	v_mfma_f32_16x16x32_f16 v[36:39], v[232:235], v[60:63], v[4:7]
	v_mfma_f32_16x16x32_f16 v[4:7], v[244:247], v[68:71], v[224:227]
	v_mfma_f32_16x16x32_f16 v[24:27], v[248:251], v[76:79], v[4:7]
	v_mfma_f32_16x16x32_f16 v[4:7], v[190:193], v[68:71], v[228:231]
	v_mfma_f32_16x16x32_f16 v[20:23], v[232:235], v[76:79], v[4:7]
	v_mfma_f32_16x16x32_f16 v[4:7], v[244:247], v[84:87], v[236:239]
	v_mfma_f32_16x16x32_f16 v[8:11], v[248:251], v[88:91], v[4:7]
	v_mfma_f32_16x16x32_f16 v[4:7], v[190:193], v[84:87], v[240:243]
	v_mfma_f32_16x16x32_f16 v[4:7], v[232:235], v[88:91], v[4:7]
	s_barrier
	s_setprio 0
	s_add_u32 s36, s36, 0x40180
	s_addc_u32 s37, s37, 0
	s_add_u32 s95, s34, 0x200
	s_addc_u32 vcc_lo, s35, 0
	s_mov_b32 vcc_hi, 0

.LBB0_1504:
	s_and_b32 s1, s1, 3
	s_lshl_b32 s59, s3, 6
	s_lshl_b32 s3, s3, 13
	s_lshl_b32 s60, s1, 5
	s_lshl_b32 s9, s1, 12
	s_add_u32 s10, s16, 0x12400000
	s_addc_u32 s11, s17, 0
	s_add_u32 s14, s16, 0x16500000
	s_addc_u32 s15, s17, 0
	s_add_u32 s16, s16, 0x1a600000
	s_addc_u32 s17, s17, 0
	s_add_u32 s18, s52, s37
	s_addc_u32 s19, s53, 0
	s_add_u32 s20, s54, s37
	s_addc_u32 s21, s55, 0
	s_add_i32 m0, s51, 0x18000
	v_lshl_add_u64 v[10:11], v[10:11], 0, s[74:75]
	s_waitcnt vmcnt(2)
	s_barrier
	global_load_lds_dwordx4 v[10:11], off
	v_lshl_add_u64 v[8:9], v[8:9], 0, s[74:75]
	s_add_i32 m0, s51, 0x1a000
	s_add_i32 s52, s51, 0x8000
	s_add_i32 s53, s51, 0xa000
	global_load_lds_dwordx4 v[8:9], off
	v_lshl_add_u64 v[4:5], v[4:5], 0, s[74:75]
	s_mov_b32 m0, s52
	s_add_u32 s22, s28, 0x40080
	global_load_lds_dwordx4 v[4:5], off
	v_lshl_add_u64 v[4:5], v[6:7], 0, s[74:75]
	s_mov_b32 m0, s53
	s_addc_u32 s23, s29, 0
	global_load_lds_dwordx4 v[4:5], off
	s_add_i32 m0, s51, 0x1c000
	v_lshl_add_u64 v[4:5], s[22:23], 0, v[160:161]
	global_load_lds_dwordx4 v[4:5], off
	v_lshl_add_u64 v[4:5], s[22:23], 0, v[164:165]
	s_add_i32 m0, s51, 0x1e000
	s_movk_i32 s13, 0x3c0
	global_load_lds_dwordx4 v[4:5], off
	v_and_b32_e32 v4, 48, v12
	v_lshlrev_b32_e32 v5, 6, v12
	v_and_or_b32 v4, v5, s13, v4
	v_and_b32_e32 v2, 32, v2
	v_bitop3_b32 v5, v4, s3, v2 bitop3:0xde
	v_bitop3_b32 v204, s9, v4, v2 bitop3:0xf6
	v_lshlrev_b32_e32 v2, 14, v13
	v_and_b32_e32 v2, 0xffff8000, v2
	v_lshl_add_u32 v2, v14, 11, v2
	v_and_b32_e32 v4, 1, v13
	v_lshl_or_b32 v2, v4, 6, v2
	v_lshl_add_u32 v166, v15, 1, v2
	v_lshlrev_b32_e32 v2, 14, v16
	v_and_b32_e32 v2, 0xffff8000, v2
	s_waitcnt vmcnt(0)
	v_lshl_add_u32 v2, v17, 11, v2
	v_and_b32_e32 v4, 1, v16
	s_cmpk_lt_u32 s0, 0x100
	v_lshl_or_b32 v2, v4, 6, v2
	s_cselect_b64 s[22:23], -1, 0
	s_lshl_b32 s64, s1, 1
	v_mov_b32_e32 v167, v3
	v_lshl_add_u32 v168, v18, 1, v2
	v_mov_b32_e32 v169, v3
	s_mov_b32 s9, 0
	v_add_u32_e32 v205, 0, v5
	s_mov_b32 s54, 0
	s_barrier
	s_branch .LBB0_1507

.LBB0_1513:
	s_ashr_i32 s27, s26, 31
	s_lshl_b64 s[0:1], s[26:27], 19
	s_add_u32 s3, s46, s0
	s_addc_u32 s13, s48, s1
	s_ashr_i32 s25, s24, 31
	s_lshl_b64 s[0:1], s[24:25], 19
	s_add_u32 s25, s49, s0
	s_addc_u32 s27, s50, s1
	s_add_i32 s55, 0, 0x10000
	s_and_b64 s[0:1], s[38:39], exec
	s_cselect_b32 s41, s13, s31
	s_cselect_b32 s40, s3, s30
	s_add_i32 s61, 0, 0x14000
	v_add_u32_e32 v2, s55, v204
	v_add_u32_e32 v112, s61, v204
	ds_read_b128 v[4:7], v2
	ds_read_b128 v[8:11], v2 offset:1024
	ds_read_b128 v[12:15], v2 offset:2048
	ds_read_b128 v[16:19], v2 offset:3072
	ds_read_b128 v[20:23], v112
	ds_read_b128 v[24:27], v112 offset:1024
	ds_read_b128 v[28:31], v112 offset:2048
	ds_read_b128 v[32:35], v112 offset:3072
	s_and_b64 s[0:1], s[38:39], exec
	v_mov_b32_e32 v253, 0x3eaaaaab
	v_mov_b32_e32 v252, 0x260
	s_cselect_b32 s43, s27, s29
	s_cselect_b32 s42, s25, s28
	s_add_u32 s34, s30, 0x40080
	s_addc_u32 s35, s31, 0
	s_add_i32 s0, s51, 0xc000
	v_lshl_add_u64 v[68:69], s[34:35], 0, v[0:1]
	s_mov_b32 m0, s0
	s_add_i32 s1, s51, 0xe000
	ds_read_b128 v[36:39], v205
	ds_read_b128 v[40:43], v205 offset:1024
	ds_read_b128 v[44:47], v205 offset:2048
	ds_read_b128 v[48:51], v205 offset:3072
	ds_read_b128 v[52:55], v205 offset:4096
	ds_read_b128 v[56:59], v205 offset:5120
	ds_read_b128 v[60:63], v205 offset:6144
	ds_read_b128 v[64:67], v205 offset:7168
	global_load_lds_dwordx4 v[68:69], off
	v_lshl_add_u64 v[68:69], s[34:35], 0, v[162:163]
	s_mov_b32 m0, s1
	s_nop 0
	global_load_lds_dwordx4 v[68:69], off
	s_waitcnt vmcnt(24)
	s_waitcnt lgkmcnt(0)
	s_setprio 1
	s_barrier
	v_mfma_f32_16x16x32_bf16 v[68:71], v[4:7], v[36:39], 0
	v_mfma_f32_16x16x32_bf16 v[72:75], v[12:15], v[36:39], 0
	v_mfma_f32_16x16x32_bf16 v[76:79], v[4:7], v[44:47], 0
	v_mfma_f32_16x16x32_bf16 v[80:83], v[12:15], v[44:47], 0
	v_mfma_f32_16x16x32_bf16 v[84:87], v[4:7], v[52:55], 0
	v_mfma_f32_16x16x32_bf16 v[88:91], v[12:15], v[52:55], 0
	v_mfma_f32_16x16x32_bf16 v[92:95], v[4:7], v[60:63], 0
	v_mfma_f32_16x16x32_bf16 v[96:99], v[12:15], v[60:63], 0
	v_mfma_f32_16x16x32_bf16 v[68:71], v[8:11], v[40:43], v[68:71]
	v_mfma_f32_16x16x32_bf16 v[72:75], v[16:19], v[40:43], v[72:75]
	v_mfma_f32_16x16x32_bf16 v[76:79], v[8:11], v[48:51], v[76:79]
	v_mfma_f32_16x16x32_bf16 v[80:83], v[16:19], v[48:51], v[80:83]
	v_mfma_f32_16x16x32_bf16 v[84:87], v[8:11], v[56:59], v[84:87]
	v_mfma_f32_16x16x32_bf16 v[88:91], v[16:19], v[56:59], v[88:91]
	v_mfma_f32_16x16x32_bf16 v[92:95], v[8:11], v[64:67], v[92:95]
	v_mfma_f32_16x16x32_bf16 v[96:99], v[16:19], v[64:67], v[96:99]
	v_mfma_f32_16x16x32_bf16 v[100:103], v[20:23], v[36:39], 0
	v_mfma_f32_16x16x32_bf16 v[36:39], v[28:31], v[36:39], 0
	v_mfma_f32_16x16x32_bf16 v[104:107], v[24:27], v[40:43], v[100:103]
	v_mfma_f32_16x16x32_bf16 v[36:39], v[32:35], v[40:43], v[36:39]
	v_mfma_f32_16x16x32_bf16 v[40:43], v[20:23], v[44:47], 0
	v_mfma_f32_16x16x32_bf16 v[44:47], v[28:31], v[44:47], 0
	v_mfma_f32_16x16x32_bf16 v[40:43], v[24:27], v[48:51], v[40:43]
	v_mfma_f32_16x16x32_bf16 v[44:47], v[32:35], v[48:51], v[44:47]
	v_mfma_f32_16x16x32_bf16 v[48:51], v[20:23], v[52:55], 0
	v_mfma_f32_16x16x32_bf16 v[52:55], v[28:31], v[52:55], 0
	v_mfma_f32_16x16x32_bf16 v[48:51], v[24:27], v[56:59], v[48:51]
	v_mfma_f32_16x16x32_bf16 v[108:111], v[32:35], v[56:59], v[52:55]
	v_mfma_f32_16x16x32_bf16 v[52:55], v[20:23], v[60:63], 0
	s_nop 0
	v_mfma_f32_16x16x32_bf16 v[120:123], v[24:27], v[64:67], v[52:55]
	v_mfma_f32_16x16x32_bf16 v[52:55], v[28:31], v[60:63], 0
	s_nop 0
	v_mfma_f32_16x16x32_bf16 v[132:135], v[32:35], v[64:67], v[52:55]
	s_barrier
	s_setprio 0
	s_add_i32 s3, s55, s45
	v_lshl_add_u64 v[198:199], s[28:29], 0, v[160:161]
	s_mov_b64 s[76:77], 0x100
	s_add_i32 s13, s3, 0x2000
	v_lshl_add_u64 v[118:119], v[198:199], 0, s[76:77]
	s_mov_b32 m0, s3
	v_lshl_add_u64 v[246:247], s[28:29], 0, v[164:165]
	s_add_u32 s34, s28, 0x40100
	ds_read_b128 v[52:55], v205 offset:16384
	ds_read_b128 v[56:59], v205 offset:17408
	ds_read_b128 v[60:63], v205 offset:18432
	ds_read_b128 v[64:67], v205 offset:19456
	ds_read_b128 v[100:103], v205 offset:20480
	ds_read_b128 v[114:117], v205 offset:21504
	ds_read_b128 v[124:127], v205 offset:22528
	ds_read_b128 v[128:131], v205 offset:23552
	global_load_lds_dwordx4 v[118:119], off
	v_lshl_add_u64 v[118:119], v[246:247], 0, s[76:77]
	s_mov_b32 m0, s13
	s_addc_u32 s35, s29, 0
	s_add_i32 s25, s61, s45
	global_load_lds_dwordx4 v[118:119], off
	v_lshl_add_u64 v[118:119], s[34:35], 0, v[160:161]
	s_mov_b32 m0, s25
	s_add_i32 s27, s25, 0x2000
	global_load_lds_dwordx4 v[118:119], off
	v_lshl_add_u64 v[118:119], s[34:35], 0, v[164:165]
	s_mov_b32 m0, s27
	v_lshl_add_u64 v[248:249], s[30:31], 0, v[0:1]
	global_load_lds_dwordx4 v[118:119], off
	v_lshl_add_u64 v[118:119], v[248:249], 0, s[76:77]
	s_mov_b32 m0, s51
	v_lshl_add_u64 v[250:251], s[30:31], 0, v[162:163]
	global_load_lds_dwordx4 v[118:119], off
	v_lshl_add_u64 v[118:119], v[250:251], 0, s[76:77]
	s_mov_b32 m0, s56
	s_nop 0
	global_load_lds_dwordx4 v[118:119], off
	s_waitcnt vmcnt(24)
	s_waitcnt lgkmcnt(0)
	s_setprio 1
	s_barrier
	v_mfma_f32_16x16x32_bf16 v[136:139], v[4:7], v[52:55], 0
	s_nop 0
	v_mfma_f32_16x16x32_bf16 v[144:147], v[8:11], v[56:59], v[136:139]
	v_mfma_f32_16x16x32_bf16 v[136:139], v[12:15], v[52:55], 0
	s_nop 0
	v_mfma_f32_16x16x32_bf16 v[148:151], v[16:19], v[56:59], v[136:139]
	v_mfma_f32_16x16x32_bf16 v[136:139], v[4:7], v[60:63], 0
	s_nop 0
	v_mfma_f32_16x16x32_bf16 v[152:155], v[8:11], v[64:67], v[136:139]
	v_mfma_f32_16x16x32_bf16 v[136:139], v[12:15], v[60:63], 0
	s_nop 0
	v_mfma_f32_16x16x32_bf16 v[156:159], v[16:19], v[64:67], v[136:139]
	v_mfma_f32_16x16x32_bf16 v[136:139], v[4:7], v[100:103], 0
	v_mfma_f32_16x16x32_bf16 v[4:7], v[4:7], v[124:127], 0
	v_mfma_f32_16x16x32_bf16 v[170:173], v[8:11], v[114:117], v[136:139]
	v_mfma_f32_16x16x32_bf16 v[4:7], v[8:11], v[128:131], v[4:7]
	v_mfma_f32_16x16x32_bf16 v[8:11], v[12:15], v[124:127], 0
	s_nop 0
	v_mfma_f32_16x16x32_bf16 v[8:11], v[16:19], v[128:131], v[8:11]
	v_mfma_f32_16x16x32_bf16 v[136:139], v[12:15], v[100:103], 0
	s_nop 0
	v_mfma_f32_16x16x32_bf16 v[174:177], v[16:19], v[114:117], v[136:139]
	v_mfma_f32_16x16x32_bf16 v[12:15], v[20:23], v[52:55], 0
	v_mfma_f32_16x16x32_bf16 v[16:19], v[28:31], v[52:55], 0
	v_mfma_f32_16x16x32_bf16 v[52:55], v[20:23], v[60:63], 0
	s_nop 0
	v_mfma_f32_16x16x32_bf16 v[178:181], v[24:27], v[64:67], v[52:55]
	v_mfma_f32_16x16x32_bf16 v[52:55], v[28:31], v[60:63], 0
	v_mfma_f32_16x16x32_bf16 v[12:15], v[24:27], v[56:59], v[12:15]
	v_mfma_f32_16x16x32_bf16 v[16:19], v[32:35], v[56:59], v[16:19]
	v_mfma_f32_16x16x32_bf16 v[182:185], v[32:35], v[64:67], v[52:55]
	v_mfma_f32_16x16x32_bf16 v[52:55], v[20:23], v[100:103], 0
	v_mfma_f32_16x16x32_bf16 v[20:23], v[20:23], v[124:127], 0
	v_mfma_f32_16x16x32_bf16 v[186:189], v[24:27], v[114:117], v[52:55]
	v_mfma_f32_16x16x32_bf16 v[52:55], v[28:31], v[100:103], 0
	v_mfma_f32_16x16x32_bf16 v[194:197], v[24:27], v[128:131], v[20:23]
	v_mfma_f32_16x16x32_bf16 v[20:23], v[28:31], v[124:127], 0
	v_mfma_f32_16x16x32_bf16 v[190:193], v[32:35], v[114:117], v[52:55]
	v_mfma_f32_16x16x32_bf16 v[200:203], v[32:35], v[128:131], v[20:23]
	s_barrier
	s_setprio 0
	s_add_i32 s55, 0, 0x18000
	s_add_i32 s62, 0, 0x1c000
	v_add_u32_e32 v113, s55, v204
	v_add_u32_e32 v114, s62, v204
	ds_read_b128 v[20:23], v113
	ds_read_b128 v[24:27], v113 offset:1024
	ds_read_b128 v[28:31], v113 offset:2048
	ds_read_b128 v[32:35], v113 offset:3072
	ds_read_b128 v[206:209], v114
	ds_read_b128 v[210:213], v114 offset:1024
	ds_read_b128 v[214:217], v114 offset:2048
	ds_read_b128 v[218:221], v114 offset:3072
	s_add_u32 s34, s30, 0x40100
	s_addc_u32 s35, s31, 0
	s_mov_b32 m0, s57
	v_lshl_add_u64 v[60:61], s[34:35], 0, v[0:1]
	ds_read_b128 v[52:55], v205 offset:32768
	ds_read_b128 v[56:59], v205 offset:33792
	ds_read_b128 v[222:225], v205 offset:34816
	ds_read_b128 v[226:229], v205 offset:35840
	ds_read_b128 v[230:233], v205 offset:36864
	ds_read_b128 v[234:237], v205 offset:37888
	ds_read_b128 v[238:241], v205 offset:38912
	ds_read_b128 v[242:245], v205 offset:39936
	global_load_lds_dwordx4 v[60:61], off
	v_lshl_add_u64 v[60:61], s[34:35], 0, v[162:163]
	s_mov_b32 m0, s58
	s_nop 0
	global_load_lds_dwordx4 v[60:61], off
	s_waitcnt vmcnt(8)
	s_waitcnt lgkmcnt(0)
	s_setprio 1
	s_barrier
	v_mfma_f32_16x16x32_bf16 v[60:63], v[20:23], v[52:55], v[68:71]
	v_mfma_f32_16x16x32_bf16 v[140:143], v[24:27], v[56:59], v[60:63]
	v_mfma_f32_16x16x32_bf16 v[60:63], v[28:31], v[52:55], v[72:75]
	v_mfma_f32_16x16x32_bf16 v[136:139], v[32:35], v[56:59], v[60:63]
	v_mfma_f32_16x16x32_bf16 v[60:63], v[20:23], v[222:225], v[76:79]
	v_mfma_f32_16x16x32_bf16 v[128:131], v[24:27], v[226:229], v[60:63]
	v_mfma_f32_16x16x32_bf16 v[60:63], v[28:31], v[222:225], v[80:83]
	v_mfma_f32_16x16x32_bf16 v[124:127], v[32:35], v[226:229], v[60:63]
	v_mfma_f32_16x16x32_bf16 v[60:63], v[20:23], v[230:233], v[84:87]
	v_mfma_f32_16x16x32_bf16 v[116:119], v[24:27], v[234:237], v[60:63]
	v_mfma_f32_16x16x32_bf16 v[60:63], v[28:31], v[230:233], v[88:91]
	v_mfma_f32_16x16x32_bf16 v[100:103], v[32:35], v[234:237], v[60:63]
	v_mfma_f32_16x16x32_bf16 v[60:63], v[20:23], v[238:241], v[92:95]
	v_mfma_f32_16x16x32_bf16 v[88:91], v[24:27], v[242:245], v[60:63]
	v_mfma_f32_16x16x32_bf16 v[60:63], v[28:31], v[238:241], v[96:99]
	v_mfma_f32_16x16x32_bf16 v[76:79], v[32:35], v[242:245], v[60:63]
	v_mfma_f32_16x16x32_bf16 v[60:63], v[206:209], v[52:55], v[104:107]
	v_mfma_f32_16x16x32_bf16 v[36:39], v[214:217], v[52:55], v[36:39]
	v_mfma_f32_16x16x32_bf16 v[64:67], v[210:213], v[56:59], v[60:63]
	v_mfma_f32_16x16x32_bf16 v[60:63], v[218:221], v[56:59], v[36:39]
	v_mfma_f32_16x16x32_bf16 v[36:39], v[206:209], v[222:225], v[40:43]
	v_mfma_f32_16x16x32_bf16 v[56:59], v[210:213], v[226:229], v[36:39]
	v_mfma_f32_16x16x32_bf16 v[36:39], v[214:217], v[222:225], v[44:47]
	v_mfma_f32_16x16x32_bf16 v[52:55], v[218:221], v[226:229], v[36:39]
	v_mfma_f32_16x16x32_bf16 v[36:39], v[206:209], v[230:233], v[48:51]
	v_mfma_f32_16x16x32_bf16 v[48:51], v[210:213], v[234:237], v[36:39]
	v_mfma_f32_16x16x32_bf16 v[36:39], v[214:217], v[230:233], v[108:111]
	v_mfma_f32_16x16x32_bf16 v[44:47], v[218:221], v[234:237], v[36:39]
	v_mfma_f32_16x16x32_bf16 v[36:39], v[206:209], v[238:241], v[120:123]
	v_mfma_f32_16x16x32_bf16 v[40:43], v[210:213], v[242:245], v[36:39]
	v_mfma_f32_16x16x32_bf16 v[36:39], v[214:217], v[238:241], v[132:135]
	v_mfma_f32_16x16x32_bf16 v[36:39], v[218:221], v[242:245], v[36:39]
	s_barrier
	s_setprio 0
	s_add_i32 s55, s55, s45
	s_add_i32 s61, s55, 0x2000
	v_lshl_add_u64 v[68:69], v[198:199], 0, s[84:85]
	s_mov_b32 m0, s55
	s_add_u32 s34, s28, 0x40180
	ds_read_b128 v[120:123], v205 offset:49152
	ds_read_b128 v[132:135], v205 offset:50176
	ds_read_b128 v[222:225], v205 offset:51200
	ds_read_b128 v[226:229], v205 offset:52224
	ds_read_b128 v[230:233], v205 offset:53248
	ds_read_b128 v[234:237], v205 offset:54272
	ds_read_b128 v[238:241], v205 offset:55296
	ds_read_b128 v[242:245], v205 offset:56320
	global_load_lds_dwordx4 v[68:69], off
	v_lshl_add_u64 v[68:69], v[246:247], 0, s[84:85]
	s_mov_b32 m0, s61
	s_addc_u32 s35, s29, 0
	s_add_i32 s62, s62, s45
	global_load_lds_dwordx4 v[68:69], off
	v_lshl_add_u64 v[68:69], s[34:35], 0, v[160:161]
	s_mov_b32 m0, s62
	s_add_i32 s76, s62, 0x2000
	global_load_lds_dwordx4 v[68:69], off
	v_lshl_add_u64 v[68:69], s[34:35], 0, v[164:165]
	s_mov_b32 m0, s76
	s_nop 0
	global_load_lds_dwordx4 v[68:69], off
	v_lshl_add_u64 v[68:69], v[248:249], 0, s[84:85]
	s_mov_b32 m0, s52
	s_nop 0
	global_load_lds_dwordx4 v[68:69], off
	v_lshl_add_u64 v[68:69], v[250:251], 0, s[84:85]
	s_mov_b32 m0, s53
	s_nop 0
	global_load_lds_dwordx4 v[68:69], off
	s_waitcnt vmcnt(8)
	s_waitcnt lgkmcnt(0)
	s_setprio 1
	s_barrier
	v_mfma_f32_16x16x32_bf16 v[68:71], v[20:23], v[120:123], v[144:147]
	v_mfma_f32_16x16x32_bf16 v[108:111], v[24:27], v[132:135], v[68:71]
	v_mfma_f32_16x16x32_bf16 v[68:71], v[28:31], v[120:123], v[148:151]
	v_mfma_f32_16x16x32_bf16 v[104:107], v[32:35], v[132:135], v[68:71]
	v_mfma_f32_16x16x32_bf16 v[68:71], v[20:23], v[222:225], v[152:155]
	v_mfma_f32_16x16x32_bf16 v[96:99], v[24:27], v[226:229], v[68:71]
	v_mfma_f32_16x16x32_bf16 v[68:71], v[28:31], v[222:225], v[156:159]
	v_mfma_f32_16x16x32_bf16 v[92:95], v[32:35], v[226:229], v[68:71]
	v_mfma_f32_16x16x32_bf16 v[68:71], v[20:23], v[230:233], v[170:173]
	v_mfma_f32_16x16x32_bf16 v[4:7], v[20:23], v[238:241], v[4:7]
	v_mfma_f32_16x16x32_bf16 v[84:87], v[24:27], v[234:237], v[68:71]
	v_mfma_f32_16x16x32_bf16 v[68:71], v[28:31], v[230:233], v[174:177]
	v_mfma_f32_16x16x32_bf16 v[72:75], v[24:27], v[242:245], v[4:7]
	v_mfma_f32_16x16x32_bf16 v[4:7], v[28:31], v[238:241], v[8:11]
	v_mfma_f32_16x16x32_bf16 v[80:83], v[32:35], v[234:237], v[68:71]
	v_mfma_f32_16x16x32_bf16 v[68:71], v[32:35], v[242:245], v[4:7]
	v_mfma_f32_16x16x32_bf16 v[4:7], v[206:209], v[120:123], v[12:15]
	v_mfma_f32_16x16x32_bf16 v[32:35], v[210:213], v[132:135], v[4:7]
	v_mfma_f32_16x16x32_bf16 v[4:7], v[214:217], v[120:123], v[16:19]
	v_mfma_f32_16x16x32_bf16 v[28:31], v[218:221], v[132:135], v[4:7]
	v_mfma_f32_16x16x32_bf16 v[4:7], v[206:209], v[222:225], v[178:181]
	v_mfma_f32_16x16x32_bf16 v[24:27], v[210:213], v[226:229], v[4:7]
	v_mfma_f32_16x16x32_bf16 v[4:7], v[214:217], v[222:225], v[182:185]
	v_mfma_f32_16x16x32_bf16 v[20:23], v[218:221], v[226:229], v[4:7]
	v_mfma_f32_16x16x32_bf16 v[4:7], v[206:209], v[230:233], v[186:189]
	v_mfma_f32_16x16x32_bf16 v[16:19], v[210:213], v[234:237], v[4:7]
	v_mfma_f32_16x16x32_bf16 v[4:7], v[214:217], v[230:233], v[190:193]
	v_mfma_f32_16x16x32_bf16 v[12:15], v[218:221], v[234:237], v[4:7]
	v_mfma_f32_16x16x32_bf16 v[4:7], v[206:209], v[238:241], v[194:197]
	v_mfma_f32_16x16x32_bf16 v[8:11], v[210:213], v[242:245], v[4:7]
	v_mfma_f32_16x16x32_bf16 v[4:7], v[214:217], v[238:241], v[200:203]
	v_mfma_f32_16x16x32_bf16 v[4:7], v[218:221], v[242:245], v[4:7]
	s_barrier
	s_setprio 0
	s_add_u32 s30, s30, 0x40180
	s_addc_u32 s31, s31, 0
	s_add_u32 s77, s28, 0x200
	s_addc_u32 s79, s29, 0
	s_mov_b32 s80, 0

.LBB0_1647:
	s_ashr_i32 s17, s16, 31
	s_lshl_b64 s[18:19], s[16:17], 19
	s_add_u32 s17, s3, s18
	s_addc_u32 s20, s30, s19
	s_ashr_i32 s15, s14, 31
	s_lshl_b64 s[18:19], s[14:15], 19
	s_add_u32 s15, s31, s18
	s_addc_u32 s23, s34, s19
	s_add_i32 s29, 0, 0x10000
	s_and_b64 s[18:19], s[38:39], exec
	s_cselect_b32 s19, s20, s27
	s_cselect_b32 s18, s17, s26
	s_add_i32 s58, 0, 0x14000
	v_add_u32_e32 v2, s29, v174
	v_add_u32_e32 v85, s58, v174
	ds_read_b128 v[4:7], v2
	ds_read_b128 v[8:11], v2 offset:1024
	ds_read_b128 v[12:15], v2 offset:2048
	ds_read_b128 v[16:19], v2 offset:3072
	ds_read_b128 v[20:23], v85
	ds_read_b128 v[24:27], v85 offset:1024
	ds_read_b128 v[28:31], v85 offset:2048
	ds_read_b128 v[32:35], v85 offset:3072
	s_and_b64 s[20:21], s[38:39], exec
	s_cselect_b32 s21, s23, s25
	s_cselect_b32 s20, s15, s24
	s_add_u32 s54, s26, 0x40080
	s_addc_u32 s55, s27, 0
	s_add_i32 s15, s44, 0xc000
	v_lshl_add_u64 v[68:69], s[54:55], 0, v[0:1]
	s_mov_b32 m0, s15
	s_add_i32 s17, s44, 0xe000
	ds_read_b128 v[36:39], v175
	ds_read_b128 v[40:43], v175 offset:1024
	ds_read_b128 v[44:47], v175 offset:2048
	ds_read_b128 v[48:51], v175 offset:3072
	ds_read_b128 v[52:55], v175 offset:4096
	ds_read_b128 v[56:59], v175 offset:5120
	ds_read_b128 v[60:63], v175 offset:6144
	ds_read_b128 v[64:67], v175 offset:7168
	global_load_lds_dwordx4 v[68:69], off
	v_lshl_add_u64 v[68:69], s[54:55], 0, v[166:167]
	s_mov_b32 m0, s17
	s_nop 0
	global_load_lds_dwordx4 v[68:69], off
	s_waitcnt vmcnt(17)
	s_waitcnt lgkmcnt(0)
	s_setprio 1
	s_barrier
	v_mfma_f32_16x16x32_bf16 v[68:71], v[4:7], v[36:39], 0
	v_mfma_f32_16x16x32_bf16 v[72:75], v[12:15], v[36:39], 0
	v_mfma_f32_16x16x32_bf16 v[76:79], v[4:7], v[44:47], 0
	v_mfma_f32_16x16x32_bf16 v[80:83], v[12:15], v[44:47], 0
	v_mfma_f32_16x16x32_bf16 v[68:71], v[8:11], v[40:43], v[68:71]
	v_mfma_f32_16x16x32_bf16 v[72:75], v[16:19], v[40:43], v[72:75]
	v_mfma_f32_16x16x32_bf16 v[76:79], v[8:11], v[48:51], v[76:79]
	v_mfma_f32_16x16x32_bf16 v[80:83], v[16:19], v[48:51], v[80:83]
	v_mfma_f32_16x16x32_bf16 v[86:89], v[4:7], v[52:55], 0
	v_mfma_f32_16x16x32_bf16 v[92:95], v[12:15], v[52:55], 0
	v_mfma_f32_16x16x32_bf16 v[96:99], v[4:7], v[60:63], 0
	v_mfma_f32_16x16x32_bf16 v[100:103], v[12:15], v[60:63], 0
	v_mfma_f32_16x16x32_bf16 v[88:91], v[8:11], v[56:59], v[86:89]
	v_mfma_f32_16x16x32_bf16 v[92:95], v[16:19], v[56:59], v[92:95]
	v_mfma_f32_16x16x32_bf16 v[96:99], v[8:11], v[64:67], v[96:99]
	v_mfma_f32_16x16x32_bf16 v[100:103], v[16:19], v[64:67], v[100:103]
	v_mfma_f32_16x16x32_bf16 v[104:107], v[20:23], v[36:39], 0
	v_mfma_f32_16x16x32_bf16 v[36:39], v[28:31], v[36:39], 0
	v_mfma_f32_16x16x32_bf16 v[104:107], v[24:27], v[40:43], v[104:107]
	v_mfma_f32_16x16x32_bf16 v[140:143], v[32:35], v[40:43], v[36:39]
	v_mfma_f32_16x16x32_bf16 v[40:43], v[20:23], v[44:47], 0
	v_mfma_f32_16x16x32_bf16 v[44:47], v[28:31], v[44:47], 0
	v_mfma_f32_16x16x32_bf16 v[144:147], v[24:27], v[48:51], v[40:43]
	v_mfma_f32_16x16x32_bf16 v[44:47], v[32:35], v[48:51], v[44:47]
	v_mfma_f32_16x16x32_bf16 v[48:51], v[20:23], v[52:55], 0
	v_mfma_f32_16x16x32_bf16 v[52:55], v[28:31], v[52:55], 0
	v_mfma_f32_16x16x32_bf16 v[48:51], v[24:27], v[56:59], v[48:51]
	v_mfma_f32_16x16x32_bf16 v[52:55], v[32:35], v[56:59], v[52:55]
	v_mfma_f32_16x16x32_bf16 v[56:59], v[20:23], v[60:63], 0
	v_mfma_f32_16x16x32_bf16 v[60:63], v[28:31], v[60:63], 0
	v_mfma_f32_16x16x32_bf16 v[56:59], v[24:27], v[64:67], v[56:59]
	v_mfma_f32_16x16x32_bf16 v[60:63], v[32:35], v[64:67], v[60:63]
	s_barrier
	s_setprio 0
	s_add_i32 s23, s29, s0
	v_lshl_add_u64 v[252:253], s[24:25], 0, v[164:165]
	s_mov_b64 s[60:61], 0x100
	s_add_i32 s53, s23, 0x2000
	v_lshl_add_u64 v[86:87], v[252:253], 0, s[60:61]
	s_mov_b32 m0, s23
	v_lshl_add_u64 v[36:37], s[24:25], 0, v[168:169]
	s_add_u32 s56, s24, 0x40100
	ds_read_b128 v[64:67], v175 offset:16384
	ds_read_b128 v[108:111], v175 offset:17408
	ds_read_b128 v[112:115], v175 offset:18432
	ds_read_b128 v[116:119], v175 offset:19456
	ds_read_b128 v[120:123], v175 offset:20480
	ds_read_b128 v[124:127], v175 offset:21504
	ds_read_b128 v[128:131], v175 offset:22528
	ds_read_b128 v[132:135], v175 offset:23552
	global_load_lds_dwordx4 v[86:87], off
	v_lshl_add_u64 v[38:39], v[36:37], 0, s[60:61]
	s_mov_b32 m0, s53
	s_addc_u32 s57, s25, 0
	s_add_i32 s54, s58, s0
	global_load_lds_dwordx4 v[38:39], off
	v_lshl_add_u64 v[38:39], s[56:57], 0, v[164:165]
	s_mov_b32 m0, s54
	s_add_i32 s55, s54, 0x2000
	global_load_lds_dwordx4 v[38:39], off
	v_lshl_add_u64 v[38:39], s[56:57], 0, v[168:169]
	s_mov_b32 m0, s55
	v_lshl_add_u64 v[40:41], s[26:27], 0, v[166:167]
	global_load_lds_dwordx4 v[38:39], off
	v_lshl_add_u64 v[38:39], s[26:27], 0, v[0:1]
	v_lshl_add_u64 v[86:87], v[38:39], 0, s[60:61]
	s_mov_b32 m0, s44
	v_lshl_add_u64 v[42:43], v[40:41], 0, s[60:61]
	global_load_lds_dwordx4 v[86:87], off
	s_mov_b32 m0, s45
	s_nop 0
	global_load_lds_dwordx4 v[42:43], off
	s_waitcnt vmcnt(17)
	s_waitcnt lgkmcnt(0)
	s_setprio 1
	s_barrier
	v_mfma_f32_16x16x32_bf16 v[136:139], v[4:7], v[64:67], 0
	s_nop 0
	v_mfma_f32_16x16x32_bf16 v[176:179], v[8:11], v[108:111], v[136:139]
	v_mfma_f32_16x16x32_bf16 v[136:139], v[12:15], v[64:67], 0
	s_nop 0
	v_mfma_f32_16x16x32_bf16 v[180:183], v[16:19], v[108:111], v[136:139]
	v_mfma_f32_16x16x32_bf16 v[136:139], v[4:7], v[112:115], 0
	s_nop 0
	v_mfma_f32_16x16x32_bf16 v[184:187], v[8:11], v[116:119], v[136:139]
	v_mfma_f32_16x16x32_bf16 v[136:139], v[12:15], v[112:115], 0
	s_nop 0
	v_mfma_f32_16x16x32_bf16 v[188:191], v[16:19], v[116:119], v[136:139]
	v_mfma_f32_16x16x32_bf16 v[136:139], v[4:7], v[120:123], 0
	v_mfma_f32_16x16x32_bf16 v[4:7], v[4:7], v[128:131], 0
	v_mfma_f32_16x16x32_bf16 v[192:195], v[8:11], v[124:127], v[136:139]
	v_mfma_f32_16x16x32_bf16 v[4:7], v[8:11], v[132:135], v[4:7]
	v_mfma_f32_16x16x32_bf16 v[8:11], v[12:15], v[128:131], 0
	v_mfma_f32_16x16x32_bf16 v[136:139], v[12:15], v[120:123], 0
	v_mfma_f32_16x16x32_bf16 v[12:15], v[16:19], v[132:135], v[8:11]
	v_mfma_f32_16x16x32_bf16 v[200:203], v[16:19], v[124:127], v[136:139]
	v_mfma_f32_16x16x32_bf16 v[8:11], v[20:23], v[64:67], 0
	s_nop 0
	v_mfma_f32_16x16x32_bf16 v[16:19], v[24:27], v[108:111], v[8:11]
	v_mfma_f32_16x16x32_bf16 v[8:11], v[28:31], v[64:67], 0
	s_nop 0
	v_mfma_f32_16x16x32_bf16 v[108:111], v[32:35], v[108:111], v[8:11]
	v_mfma_f32_16x16x32_bf16 v[8:11], v[20:23], v[112:115], 0
	s_nop 0
	v_mfma_f32_16x16x32_bf16 v[204:207], v[24:27], v[116:119], v[8:11]
	v_mfma_f32_16x16x32_bf16 v[8:11], v[28:31], v[112:115], 0
	s_nop 0
	v_mfma_f32_16x16x32_bf16 v[112:115], v[32:35], v[116:119], v[8:11]
	v_mfma_f32_16x16x32_bf16 v[8:11], v[20:23], v[120:123], 0
	s_nop 0
	v_mfma_f32_16x16x32_bf16 v[208:211], v[24:27], v[124:127], v[8:11]
	v_mfma_f32_16x16x32_bf16 v[8:11], v[28:31], v[120:123], 0
	s_nop 0
	v_mfma_f32_16x16x32_bf16 v[212:215], v[32:35], v[124:127], v[8:11]
	v_mfma_f32_16x16x32_bf16 v[8:11], v[20:23], v[128:131], 0
	s_nop 0
	v_mfma_f32_16x16x32_bf16 v[216:219], v[24:27], v[132:135], v[8:11]
	v_mfma_f32_16x16x32_bf16 v[8:11], v[28:31], v[128:131], 0
	s_nop 0
	v_mfma_f32_16x16x32_bf16 v[220:223], v[32:35], v[132:135], v[8:11]
	s_barrier
	s_setprio 0
	s_add_i32 s29, 0, 0x18000
	s_add_i32 s58, 0, 0x1c000
	v_add_u32_e32 v86, s29, v174
	v_add_u32_e32 v87, s58, v174
	ds_read_b128 v[8:11], v86
	ds_read_b128 v[28:31], v86 offset:1024
	ds_read_b128 v[32:35], v86 offset:2048
	ds_read_b128 v[64:67], v86 offset:3072
	ds_read_b128 v[224:227], v87
	ds_read_b128 v[228:231], v87 offset:1024
	ds_read_b128 v[232:235], v87 offset:2048
	ds_read_b128 v[236:239], v87 offset:3072
	s_add_u32 s56, s26, 0x40100
	s_addc_u32 s57, s27, 0
	s_mov_b32 m0, s46
	v_lshl_add_u64 v[42:43], s[56:57], 0, v[0:1]
	ds_read_b128 v[20:23], v175 offset:32768
	ds_read_b128 v[24:27], v175 offset:33792
	ds_read_b128 v[124:127], v175 offset:34816
	ds_read_b128 v[128:131], v175 offset:35840
	ds_read_b128 v[240:243], v175 offset:36864
	ds_read_b128 v[244:247], v175 offset:37888
	ds_read_b128 v[248:251], v175 offset:38912
	ds_read_b128 v[196:199], v175 offset:39936
	global_load_lds_dwordx4 v[42:43], off
	v_lshl_add_u64 v[42:43], s[56:57], 0, v[166:167]
	s_mov_b32 m0, s48
	s_nop 0
	global_load_lds_dwordx4 v[42:43], off
	s_waitcnt vmcnt(8)
	s_waitcnt lgkmcnt(0)
	s_setprio 1
	s_barrier
	v_mfma_f32_16x16x32_bf16 v[68:71], v[8:11], v[20:23], v[68:71]
	v_mfma_f32_16x16x32_bf16 v[152:155], v[28:31], v[24:27], v[68:71]
	v_mfma_f32_16x16x32_bf16 v[68:71], v[32:35], v[20:23], v[72:75]
	v_mfma_f32_16x16x32_bf16 v[148:151], v[64:67], v[24:27], v[68:71]
	v_mfma_f32_16x16x32_bf16 v[68:71], v[8:11], v[124:127], v[76:79]
	v_mfma_f32_16x16x32_bf16 v[136:139], v[28:31], v[128:131], v[68:71]
	v_mfma_f32_16x16x32_bf16 v[68:71], v[32:35], v[124:127], v[80:83]
	v_mfma_f32_16x16x32_bf16 v[132:135], v[64:67], v[128:131], v[68:71]
	v_mfma_f32_16x16x32_bf16 v[68:71], v[8:11], v[240:243], v[88:91]
	v_mfma_f32_16x16x32_bf16 v[120:123], v[28:31], v[244:247], v[68:71]
	v_mfma_f32_16x16x32_bf16 v[68:71], v[32:35], v[240:243], v[92:95]
	v_mfma_f32_16x16x32_bf16 v[116:119], v[64:67], v[244:247], v[68:71]
	v_mfma_f32_16x16x32_bf16 v[68:71], v[8:11], v[248:251], v[96:99]
	v_mfma_f32_16x16x32_bf16 v[72:75], v[28:31], v[196:199], v[68:71]
	v_mfma_f32_16x16x32_bf16 v[68:71], v[32:35], v[248:251], v[100:103]
	v_mfma_f32_16x16x32_bf16 v[68:71], v[64:67], v[196:199], v[68:71]
	v_mfma_f32_16x16x32_bf16 v[76:79], v[224:227], v[20:23], v[104:107]
	v_mfma_f32_16x16x32_bf16 v[20:23], v[232:235], v[20:23], v[140:143]
	v_mfma_f32_16x16x32_bf16 v[156:159], v[236:239], v[24:27], v[20:23]
	v_mfma_f32_16x16x32_bf16 v[20:23], v[224:227], v[124:127], v[144:147]
	v_mfma_f32_16x16x32_bf16 v[144:147], v[228:231], v[128:131], v[20:23]
	v_mfma_f32_16x16x32_bf16 v[20:23], v[232:235], v[124:127], v[44:47]
	v_mfma_f32_16x16x32_bf16 v[140:143], v[236:239], v[128:131], v[20:23]
	v_mfma_f32_16x16x32_bf16 v[20:23], v[224:227], v[240:243], v[48:51]
	v_mfma_f32_16x16x32_bf16 v[128:131], v[228:231], v[244:247], v[20:23]
	v_mfma_f32_16x16x32_bf16 v[20:23], v[232:235], v[240:243], v[52:55]
	v_mfma_f32_16x16x32_bf16 v[124:127], v[236:239], v[244:247], v[20:23]
	v_mfma_f32_16x16x32_bf16 v[20:23], v[224:227], v[248:251], v[56:59]
	v_mfma_f32_16x16x32_bf16 v[80:83], v[228:231], v[196:199], v[20:23]
	v_mfma_f32_16x16x32_bf16 v[20:23], v[232:235], v[248:251], v[60:63]
	v_mfma_f32_16x16x32_bf16 v[160:163], v[228:231], v[24:27], v[76:79]
	v_mfma_f32_16x16x32_bf16 v[76:79], v[236:239], v[196:199], v[20:23]
	s_barrier
	s_setprio 0
	s_add_i32 s56, s29, s0
	s_add_i32 s57, s56, 0x2000
	s_nop 1
	v_lshl_add_u64 v[20:21], v[252:253], 0, s[84:85]
	s_mov_b32 m0, s56
	s_add_u32 s60, s24, 0x40180
	ds_read_b128 v[44:47], v175 offset:49152
	ds_read_b128 v[48:51], v175 offset:50176
	ds_read_b128 v[88:91], v175 offset:51200
	ds_read_b128 v[92:95], v175 offset:52224
	ds_read_b128 v[96:99], v175 offset:53248
	ds_read_b128 v[100:103], v175 offset:54272
	ds_read_b128 v[104:107], v175 offset:55296
	ds_read_b128 v[196:199], v175 offset:56320
	global_load_lds_dwordx4 v[20:21], off
	v_lshl_add_u64 v[20:21], v[36:37], 0, s[84:85]
	s_mov_b32 m0, s57
	s_addc_u32 s61, s25, 0
	s_add_i32 s58, s58, s0
	global_load_lds_dwordx4 v[20:21], off
	v_lshl_add_u64 v[20:21], s[60:61], 0, v[164:165]
	s_mov_b32 m0, s58
	s_add_i32 s59, s58, 0x2000
	global_load_lds_dwordx4 v[20:21], off
	v_lshl_add_u64 v[20:21], s[60:61], 0, v[168:169]
	s_mov_b32 m0, s59
	s_nop 0
	global_load_lds_dwordx4 v[20:21], off
	v_lshl_add_u64 v[20:21], v[38:39], 0, s[84:85]
	s_mov_b32 m0, s49
	s_nop 0
	global_load_lds_dwordx4 v[20:21], off
	v_lshl_add_u64 v[20:21], v[40:41], 0, s[84:85]
	s_mov_b32 m0, s50
	s_nop 0
	global_load_lds_dwordx4 v[20:21], off
	s_waitcnt vmcnt(8)
	s_waitcnt lgkmcnt(0)
	s_setprio 1
	s_barrier
	v_mfma_f32_16x16x32_bf16 v[20:23], v[8:11], v[44:47], v[176:179]
	v_mfma_f32_16x16x32_bf16 v[56:59], v[28:31], v[48:51], v[20:23]
	v_mfma_f32_16x16x32_bf16 v[20:23], v[32:35], v[44:47], v[180:183]
	v_mfma_f32_16x16x32_bf16 v[52:55], v[64:67], v[48:51], v[20:23]
	v_mfma_f32_16x16x32_bf16 v[20:23], v[8:11], v[88:91], v[184:187]
	v_mfma_f32_16x16x32_bf16 v[40:43], v[28:31], v[92:95], v[20:23]
	v_mfma_f32_16x16x32_bf16 v[20:23], v[32:35], v[88:91], v[188:191]
	v_mfma_f32_16x16x32_bf16 v[36:39], v[64:67], v[92:95], v[20:23]
	v_mfma_f32_16x16x32_bf16 v[20:23], v[8:11], v[96:99], v[192:195]
	v_mfma_f32_16x16x32_bf16 v[4:7], v[8:11], v[104:107], v[4:7]
	v_mfma_f32_16x16x32_bf16 v[24:27], v[28:31], v[100:103], v[20:23]
	v_mfma_f32_16x16x32_bf16 v[20:23], v[32:35], v[96:99], v[200:203]
	v_mfma_f32_16x16x32_bf16 v[8:11], v[28:31], v[196:199], v[4:7]
	v_mfma_f32_16x16x32_bf16 v[4:7], v[32:35], v[104:107], v[12:15]
	v_mfma_f32_16x16x32_bf16 v[20:23], v[64:67], v[100:103], v[20:23]
	v_mfma_f32_16x16x32_bf16 v[4:7], v[64:67], v[196:199], v[4:7]
	v_mfma_f32_16x16x32_bf16 v[12:15], v[224:227], v[44:47], v[16:19]
	v_mfma_f32_16x16x32_bf16 v[64:67], v[228:231], v[48:51], v[12:15]
	v_mfma_f32_16x16x32_bf16 v[12:15], v[232:235], v[44:47], v[108:111]
	v_mfma_f32_16x16x32_bf16 v[60:63], v[236:239], v[48:51], v[12:15]
	v_mfma_f32_16x16x32_bf16 v[12:15], v[224:227], v[88:91], v[204:207]
	v_mfma_f32_16x16x32_bf16 v[48:51], v[228:231], v[92:95], v[12:15]
	v_mfma_f32_16x16x32_bf16 v[12:15], v[232:235], v[88:91], v[112:115]
	v_mfma_f32_16x16x32_bf16 v[44:47], v[236:239], v[92:95], v[12:15]
	v_mfma_f32_16x16x32_bf16 v[12:15], v[224:227], v[96:99], v[208:211]
	v_mfma_f32_16x16x32_bf16 v[32:35], v[228:231], v[100:103], v[12:15]
	v_mfma_f32_16x16x32_bf16 v[12:15], v[232:235], v[96:99], v[212:215]
	v_mfma_f32_16x16x32_bf16 v[28:31], v[236:239], v[100:103], v[12:15]
	v_mfma_f32_16x16x32_bf16 v[12:15], v[224:227], v[104:107], v[216:219]
	v_mfma_f32_16x16x32_bf16 v[16:19], v[228:231], v[196:199], v[12:15]
	v_mfma_f32_16x16x32_bf16 v[12:15], v[232:235], v[104:107], v[220:223]
	v_mfma_f32_16x16x32_bf16 v[12:15], v[236:239], v[196:199], v[12:15]
	s_barrier
	s_setprio 0
	s_lshl_b32 s28, s28, 11
	s_and_b32 s28, s28, 0x800
	s_add_i32 s60, s28, 0
	s_add_i32 s60, s60, 0x25a00
	s_lshl_b32 s28, s43, 2
	s_add_i32 s28, s60, s28
	s_add_u32 s26, s26, 0x40180
	s_addc_u32 s27, s27, 0
	v_mbcnt_lo_u32_b32 v88, -1, 0
	v_mbcnt_hi_u32_b32 v88, -1, v88
	s_add_u32 s61, s24, 0x200
	v_lshl_add_u32 v88, v88, 2, s28
	s_addc_u32 s62, s25, 0
	s_mov_b32 s76, 0
	s_waitcnt vmcnt(8)
	ds_write_b32 v88, v84

.LBB0_1749:
	s_and_b32 s1, s1, 3
	s_lshl_b32 s50, s3, 6
	s_lshl_b32 s3, s3, 13
	s_lshl_b32 s51, s1, 5
	s_lshl_b32 s20, s1, 12
	s_add_u32 s8, s12, 0x12400000
	s_addc_u32 s9, s13, 0
	s_add_u32 s10, s12, 0x16500000
	s_addc_u32 s11, s13, 0
	s_add_u32 s12, s12, 0x1af00000
	s_addc_u32 s13, s13, 0
	s_add_u32 s14, s52, s31
	s_addc_u32 s15, s53, 0
	s_add_u32 s16, s54, s31
	s_addc_u32 s17, s55, 0
	s_add_i32 m0, s44, 0x18000
	v_lshl_add_u64 v[10:11], v[10:11], 0, s[74:75]
	s_waitcnt vmcnt(2)
	s_barrier
	global_load_lds_dwordx4 v[10:11], off
	v_lshl_add_u64 v[8:9], v[8:9], 0, s[74:75]
	s_add_i32 m0, s44, 0x1a000
	s_add_i32 s52, s44, 0x8000
	s_add_i32 s53, s44, 0xa000
	global_load_lds_dwordx4 v[8:9], off
	v_lshl_add_u64 v[4:5], v[4:5], 0, s[74:75]
	s_mov_b32 m0, s52
	s_add_u32 s18, s26, 0xb0080
	global_load_lds_dwordx4 v[4:5], off
	v_lshl_add_u64 v[4:5], v[6:7], 0, s[74:75]
	s_mov_b32 m0, s53
	s_addc_u32 s19, s27, 0
	global_load_lds_dwordx4 v[4:5], off
	s_add_i32 m0, s44, 0x1c000
	v_lshl_add_u64 v[4:5], s[18:19], 0, v[160:161]
	global_load_lds_dwordx4 v[4:5], off
	v_lshl_add_u64 v[4:5], s[18:19], 0, v[164:165]
	s_add_i32 m0, s44, 0x1e000
	s_movk_i32 s18, 0x3c0
	global_load_lds_dwordx4 v[4:5], off
	v_and_b32_e32 v4, 48, v12
	v_lshlrev_b32_e32 v5, 6, v12
	v_and_or_b32 v4, v5, s18, v4
	v_and_b32_e32 v2, 32, v2
	v_bitop3_b32 v6, v4, s3, v2 bitop3:0xde
	s_movk_i32 s3, 0xb00
	v_bitop3_b32 v204, s20, v4, v2 bitop3:0xf6
	s_cmpk_lt_u32 s0, 0x100
	v_lshrrev_b32_e32 v4, 1, v13
	v_mul_lo_u32 v2, v15, s3
	s_mov_b32 s20, 0xb000
	s_cselect_b64 s[18:19], -1, 0
	s_lshl_b32 s64, s1, 1
	v_mad_u64_u32 v[4:5], s[0:1], v4, s20, v[2:3]
	v_or_b32_e32 v2, v4, v14
	v_add_lshl_u32 v2, v2, v16, 1
	s_mov_b64 s[22:23], 0xb0180
	v_lshl_add_u64 v[166:167], v[2:3], 0, s[22:23]
	v_lshrrev_b32_e32 v4, 1, v17
	v_mul_lo_u32 v2, v19, s3
	v_mad_u64_u32 v[4:5], s[0:1], v4, s20, v[2:3]
	s_waitcnt vmcnt(0)
	v_or_b32_e32 v2, v4, v18
	v_add_lshl_u32 v2, v2, v20, 1
	v_lshl_add_u64 v[168:169], v[2:3], 0, s[22:23]
	s_mov_b32 s58, 0
	v_add_u32_e32 v205, 0, v6
	s_mov_b32 s54, 0
	s_barrier
	s_branch .LBB0_1752

.LBB0_1762:
	s_add_i32 s3, 0, 0x10000
	s_add_i32 s41, 0, 0x14000
	v_add_u32_e32 v2, s3, v204
	v_add_u32_e32 v112, s41, v204
	ds_read_b128 v[4:7], v2
	ds_read_b128 v[8:11], v2 offset:1024
	ds_read_b128 v[12:15], v2 offset:2048
	ds_read_b128 v[16:19], v2 offset:3072
	ds_read_b128 v[20:23], v112
	ds_read_b128 v[24:27], v112 offset:1024
	ds_read_b128 v[28:31], v112 offset:2048
	ds_read_b128 v[32:35], v112 offset:3072
	s_add_u32 s28, s24, 0xb0080
	s_addc_u32 s29, s25, 0
	s_add_i32 s0, s44, 0xc000
	v_lshl_add_u64 v[68:69], s[28:29], 0, v[0:1]
	s_mov_b32 m0, s0
	s_add_i32 s1, s44, 0xe000
	ds_read_b128 v[36:39], v205
	ds_read_b128 v[40:43], v205 offset:1024
	ds_read_b128 v[44:47], v205 offset:2048
	ds_read_b128 v[48:51], v205 offset:3072
	ds_read_b128 v[52:55], v205 offset:4096
	ds_read_b128 v[56:59], v205 offset:5120
	ds_read_b128 v[60:63], v205 offset:6144
	ds_read_b128 v[64:67], v205 offset:7168
	global_load_lds_dwordx4 v[68:69], off
	v_lshl_add_u64 v[68:69], s[28:29], 0, v[162:163]
	s_mov_b32 m0, s1
	s_nop 0
	global_load_lds_dwordx4 v[68:69], off
	s_waitcnt vmcnt(24)
	s_waitcnt lgkmcnt(0)
	s_setprio 1
	s_barrier
	v_mfma_f32_16x16x32_bf16 v[68:71], v[4:7], v[36:39], 0
	v_mfma_f32_16x16x32_bf16 v[72:75], v[12:15], v[36:39], 0
	v_mfma_f32_16x16x32_bf16 v[76:79], v[4:7], v[44:47], 0
	v_mfma_f32_16x16x32_bf16 v[80:83], v[12:15], v[44:47], 0
	v_mfma_f32_16x16x32_bf16 v[84:87], v[4:7], v[52:55], 0
	v_mfma_f32_16x16x32_bf16 v[88:91], v[12:15], v[52:55], 0
	v_mfma_f32_16x16x32_bf16 v[92:95], v[4:7], v[60:63], 0
	v_mfma_f32_16x16x32_bf16 v[96:99], v[12:15], v[60:63], 0
	v_mfma_f32_16x16x32_bf16 v[68:71], v[8:11], v[40:43], v[68:71]
	v_mfma_f32_16x16x32_bf16 v[72:75], v[16:19], v[40:43], v[72:75]
	v_mfma_f32_16x16x32_bf16 v[76:79], v[8:11], v[48:51], v[76:79]
	v_mfma_f32_16x16x32_bf16 v[80:83], v[16:19], v[48:51], v[80:83]
	v_mfma_f32_16x16x32_bf16 v[84:87], v[8:11], v[56:59], v[84:87]
	v_mfma_f32_16x16x32_bf16 v[88:91], v[16:19], v[56:59], v[88:91]
	v_mfma_f32_16x16x32_bf16 v[92:95], v[8:11], v[64:67], v[92:95]
	v_mfma_f32_16x16x32_bf16 v[96:99], v[16:19], v[64:67], v[96:99]
	v_mfma_f32_16x16x32_bf16 v[100:103], v[20:23], v[36:39], 0
	v_mfma_f32_16x16x32_bf16 v[36:39], v[28:31], v[36:39], 0
	v_mfma_f32_16x16x32_bf16 v[104:107], v[24:27], v[40:43], v[100:103]
	v_mfma_f32_16x16x32_bf16 v[36:39], v[32:35], v[40:43], v[36:39]
	v_mfma_f32_16x16x32_bf16 v[40:43], v[20:23], v[44:47], 0
	v_mfma_f32_16x16x32_bf16 v[44:47], v[28:31], v[44:47], 0
	v_mfma_f32_16x16x32_bf16 v[40:43], v[24:27], v[48:51], v[40:43]
	v_mfma_f32_16x16x32_bf16 v[44:47], v[32:35], v[48:51], v[44:47]
	v_mfma_f32_16x16x32_bf16 v[48:51], v[20:23], v[52:55], 0
	v_mfma_f32_16x16x32_bf16 v[52:55], v[28:31], v[52:55], 0
	v_mfma_f32_16x16x32_bf16 v[48:51], v[24:27], v[56:59], v[48:51]
	v_mfma_f32_16x16x32_bf16 v[108:111], v[32:35], v[56:59], v[52:55]
	v_mfma_f32_16x16x32_bf16 v[52:55], v[20:23], v[60:63], 0
	s_nop 0
	v_mfma_f32_16x16x32_bf16 v[120:123], v[24:27], v[64:67], v[52:55]
	v_mfma_f32_16x16x32_bf16 v[52:55], v[28:31], v[60:63], 0
	s_nop 0
	v_mfma_f32_16x16x32_bf16 v[132:135], v[32:35], v[64:67], v[52:55]
	s_barrier
	s_setprio 0
	s_add_i32 s3, s3, s35
	v_lshl_add_u64 v[202:203], s[26:27], 0, v[160:161]
	s_mov_b64 s[60:61], 0x100
	s_add_i32 s40, s3, 0x2000
	v_lshl_add_u64 v[118:119], v[202:203], 0, s[60:61]
	s_mov_b32 m0, s3
	v_lshl_add_u64 v[246:247], s[26:27], 0, v[164:165]
	s_add_u32 s28, s26, 0xb0100
	ds_read_b128 v[52:55], v205 offset:16384
	ds_read_b128 v[56:59], v205 offset:17408
	ds_read_b128 v[60:63], v205 offset:18432
	ds_read_b128 v[64:67], v205 offset:19456
	ds_read_b128 v[100:103], v205 offset:20480
	ds_read_b128 v[114:117], v205 offset:21504
	ds_read_b128 v[124:127], v205 offset:22528
	ds_read_b128 v[128:131], v205 offset:23552
	global_load_lds_dwordx4 v[118:119], off
	v_lshl_add_u64 v[118:119], v[246:247], 0, s[60:61]
	s_mov_b32 m0, s40
	s_addc_u32 s29, s27, 0
	s_add_i32 s41, s41, s35
	global_load_lds_dwordx4 v[118:119], off
	v_lshl_add_u64 v[118:119], s[28:29], 0, v[160:161]
	s_mov_b32 m0, s41
	s_add_i32 s59, s41, 0x2000
	global_load_lds_dwordx4 v[118:119], off
	v_lshl_add_u64 v[118:119], s[28:29], 0, v[164:165]
	s_mov_b32 m0, s59
	v_lshl_add_u64 v[248:249], s[24:25], 0, v[0:1]
	global_load_lds_dwordx4 v[118:119], off
	v_lshl_add_u64 v[118:119], v[248:249], 0, s[60:61]
	s_mov_b32 m0, s44
	v_lshl_add_u64 v[250:251], s[24:25], 0, v[162:163]
	global_load_lds_dwordx4 v[118:119], off
	v_lshl_add_u64 v[118:119], v[250:251], 0, s[60:61]
	s_mov_b32 m0, s45
	s_nop 0
	global_load_lds_dwordx4 v[118:119], off
	s_waitcnt vmcnt(24)
	s_waitcnt lgkmcnt(0)
	s_setprio 1
	s_barrier
	v_mfma_f32_16x16x32_bf16 v[136:139], v[4:7], v[52:55], 0
	s_nop 0
	v_mfma_f32_16x16x32_bf16 v[144:147], v[8:11], v[56:59], v[136:139]
	v_mfma_f32_16x16x32_bf16 v[136:139], v[12:15], v[52:55], 0
	s_nop 0
	v_mfma_f32_16x16x32_bf16 v[148:151], v[16:19], v[56:59], v[136:139]
	v_mfma_f32_16x16x32_bf16 v[136:139], v[4:7], v[60:63], 0
	s_nop 0
	v_mfma_f32_16x16x32_bf16 v[152:155], v[8:11], v[64:67], v[136:139]
	v_mfma_f32_16x16x32_bf16 v[136:139], v[12:15], v[60:63], 0
	s_nop 0
	v_mfma_f32_16x16x32_bf16 v[156:159], v[16:19], v[64:67], v[136:139]
	v_mfma_f32_16x16x32_bf16 v[136:139], v[4:7], v[100:103], 0
	v_mfma_f32_16x16x32_bf16 v[4:7], v[4:7], v[124:127], 0
	v_mfma_f32_16x16x32_bf16 v[170:173], v[8:11], v[114:117], v[136:139]
	v_mfma_f32_16x16x32_bf16 v[4:7], v[8:11], v[128:131], v[4:7]
	v_mfma_f32_16x16x32_bf16 v[8:11], v[12:15], v[124:127], 0
	s_nop 0
	v_mfma_f32_16x16x32_bf16 v[8:11], v[16:19], v[128:131], v[8:11]
	v_mfma_f32_16x16x32_bf16 v[136:139], v[12:15], v[100:103], 0
	s_nop 0
	v_mfma_f32_16x16x32_bf16 v[174:177], v[16:19], v[114:117], v[136:139]
	v_mfma_f32_16x16x32_bf16 v[12:15], v[20:23], v[52:55], 0
	v_mfma_f32_16x16x32_bf16 v[16:19], v[28:31], v[52:55], 0
	v_mfma_f32_16x16x32_bf16 v[52:55], v[20:23], v[60:63], 0
	s_nop 0
	v_mfma_f32_16x16x32_bf16 v[178:181], v[24:27], v[64:67], v[52:55]
	v_mfma_f32_16x16x32_bf16 v[52:55], v[28:31], v[60:63], 0
	v_mfma_f32_16x16x32_bf16 v[12:15], v[24:27], v[56:59], v[12:15]
	v_mfma_f32_16x16x32_bf16 v[16:19], v[32:35], v[56:59], v[16:19]
	v_mfma_f32_16x16x32_bf16 v[182:185], v[32:35], v[64:67], v[52:55]
	v_mfma_f32_16x16x32_bf16 v[52:55], v[20:23], v[100:103], 0
	v_mfma_f32_16x16x32_bf16 v[20:23], v[20:23], v[124:127], 0
	v_mfma_f32_16x16x32_bf16 v[186:189], v[24:27], v[114:117], v[52:55]
	v_mfma_f32_16x16x32_bf16 v[52:55], v[28:31], v[100:103], 0
	v_mfma_f32_16x16x32_bf16 v[194:197], v[24:27], v[128:131], v[20:23]
	v_mfma_f32_16x16x32_bf16 v[20:23], v[28:31], v[124:127], 0
	v_mfma_f32_16x16x32_bf16 v[190:193], v[32:35], v[114:117], v[52:55]
	v_mfma_f32_16x16x32_bf16 v[198:201], v[32:35], v[128:131], v[20:23]
	s_barrier
	s_setprio 0
	s_add_i32 s60, 0, 0x18000
	s_add_i32 s62, 0, 0x1c000
	v_add_u32_e32 v113, s60, v204
	v_add_u32_e32 v114, s62, v204
	ds_read_b128 v[20:23], v113
	ds_read_b128 v[24:27], v113 offset:1024
	ds_read_b128 v[28:31], v113 offset:2048
	ds_read_b128 v[32:35], v113 offset:3072
	ds_read_b128 v[206:209], v114
	ds_read_b128 v[210:213], v114 offset:1024
	ds_read_b128 v[214:217], v114 offset:2048
	ds_read_b128 v[218:221], v114 offset:3072
	s_add_u32 s28, s24, 0xb0100
	s_addc_u32 s29, s25, 0
	s_mov_b32 m0, s46
	v_lshl_add_u64 v[60:61], s[28:29], 0, v[0:1]
	ds_read_b128 v[52:55], v205 offset:32768
	ds_read_b128 v[56:59], v205 offset:33792
	ds_read_b128 v[222:225], v205 offset:34816
	ds_read_b128 v[226:229], v205 offset:35840
	ds_read_b128 v[230:233], v205 offset:36864
	ds_read_b128 v[234:237], v205 offset:37888
	ds_read_b128 v[238:241], v205 offset:38912
	ds_read_b128 v[242:245], v205 offset:39936
	global_load_lds_dwordx4 v[60:61], off
	v_lshl_add_u64 v[60:61], s[28:29], 0, v[162:163]
	s_mov_b32 m0, s48
	s_nop 0
	global_load_lds_dwordx4 v[60:61], off
	s_waitcnt vmcnt(8)
	s_waitcnt lgkmcnt(0)
	s_setprio 1
	s_barrier
	v_mfma_f32_16x16x32_bf16 v[60:63], v[20:23], v[52:55], v[68:71]
	v_mfma_f32_16x16x32_bf16 v[140:143], v[24:27], v[56:59], v[60:63]
	v_mfma_f32_16x16x32_bf16 v[60:63], v[28:31], v[52:55], v[72:75]
	v_mfma_f32_16x16x32_bf16 v[136:139], v[32:35], v[56:59], v[60:63]
	v_mfma_f32_16x16x32_bf16 v[60:63], v[20:23], v[222:225], v[76:79]
	v_mfma_f32_16x16x32_bf16 v[128:131], v[24:27], v[226:229], v[60:63]
	v_mfma_f32_16x16x32_bf16 v[60:63], v[28:31], v[222:225], v[80:83]
	v_mfma_f32_16x16x32_bf16 v[124:127], v[32:35], v[226:229], v[60:63]
	v_mfma_f32_16x16x32_bf16 v[60:63], v[20:23], v[230:233], v[84:87]
	v_mfma_f32_16x16x32_bf16 v[116:119], v[24:27], v[234:237], v[60:63]
	v_mfma_f32_16x16x32_bf16 v[60:63], v[28:31], v[230:233], v[88:91]
	v_mfma_f32_16x16x32_bf16 v[100:103], v[32:35], v[234:237], v[60:63]
	v_mfma_f32_16x16x32_bf16 v[60:63], v[20:23], v[238:241], v[92:95]
	v_mfma_f32_16x16x32_bf16 v[88:91], v[24:27], v[242:245], v[60:63]
	v_mfma_f32_16x16x32_bf16 v[60:63], v[28:31], v[238:241], v[96:99]
	v_mfma_f32_16x16x32_bf16 v[76:79], v[32:35], v[242:245], v[60:63]
	v_mfma_f32_16x16x32_bf16 v[60:63], v[206:209], v[52:55], v[104:107]
	v_mfma_f32_16x16x32_bf16 v[36:39], v[214:217], v[52:55], v[36:39]
	v_mfma_f32_16x16x32_bf16 v[64:67], v[210:213], v[56:59], v[60:63]
	v_mfma_f32_16x16x32_bf16 v[60:63], v[218:221], v[56:59], v[36:39]
	v_mfma_f32_16x16x32_bf16 v[36:39], v[206:209], v[222:225], v[40:43]
	v_mfma_f32_16x16x32_bf16 v[56:59], v[210:213], v[226:229], v[36:39]
	v_mfma_f32_16x16x32_bf16 v[36:39], v[214:217], v[222:225], v[44:47]
	v_mfma_f32_16x16x32_bf16 v[52:55], v[218:221], v[226:229], v[36:39]
	v_mfma_f32_16x16x32_bf16 v[36:39], v[206:209], v[230:233], v[48:51]
	v_mfma_f32_16x16x32_bf16 v[48:51], v[210:213], v[234:237], v[36:39]
	v_mfma_f32_16x16x32_bf16 v[36:39], v[214:217], v[230:233], v[108:111]
	v_mfma_f32_16x16x32_bf16 v[44:47], v[218:221], v[234:237], v[36:39]
	v_mfma_f32_16x16x32_bf16 v[36:39], v[206:209], v[238:241], v[120:123]
	v_mfma_f32_16x16x32_bf16 v[40:43], v[210:213], v[242:245], v[36:39]
	v_mfma_f32_16x16x32_bf16 v[36:39], v[214:217], v[238:241], v[132:135]
	v_mfma_f32_16x16x32_bf16 v[36:39], v[218:221], v[242:245], v[36:39]
	s_barrier
	s_setprio 0
	s_add_i32 s60, s60, s35
	s_add_i32 s61, s60, 0x2000
	v_lshl_add_u64 v[68:69], v[202:203], 0, s[84:85]
	s_mov_b32 m0, s60
	s_add_u32 s28, s26, 0xb0180
	ds_read_b128 v[120:123], v205 offset:49152
	ds_read_b128 v[132:135], v205 offset:50176
	ds_read_b128 v[222:225], v205 offset:51200
	ds_read_b128 v[226:229], v205 offset:52224
	ds_read_b128 v[230:233], v205 offset:53248
	ds_read_b128 v[234:237], v205 offset:54272
	ds_read_b128 v[238:241], v205 offset:55296
	ds_read_b128 v[242:245], v205 offset:56320
	global_load_lds_dwordx4 v[68:69], off
	v_lshl_add_u64 v[68:69], v[246:247], 0, s[84:85]
	s_mov_b32 m0, s61
	s_addc_u32 s29, s27, 0
	s_add_i32 s62, s62, s35
	global_load_lds_dwordx4 v[68:69], off
	v_lshl_add_u64 v[68:69], s[28:29], 0, v[160:161]
	s_mov_b32 m0, s62
	s_add_i32 s76, s62, 0x2000
	global_load_lds_dwordx4 v[68:69], off
	v_lshl_add_u64 v[68:69], s[28:29], 0, v[164:165]
	s_mov_b32 m0, s76
	s_nop 0
	global_load_lds_dwordx4 v[68:69], off
	v_lshl_add_u64 v[68:69], v[248:249], 0, s[84:85]
	s_mov_b32 m0, s52
	s_nop 0
	global_load_lds_dwordx4 v[68:69], off
	v_lshl_add_u64 v[68:69], v[250:251], 0, s[84:85]
	s_mov_b32 m0, s53
	s_nop 0
	global_load_lds_dwordx4 v[68:69], off
	s_waitcnt vmcnt(8)
	s_waitcnt lgkmcnt(0)
	s_setprio 1
	s_barrier
	v_mfma_f32_16x16x32_bf16 v[68:71], v[20:23], v[120:123], v[144:147]
	v_mfma_f32_16x16x32_bf16 v[108:111], v[24:27], v[132:135], v[68:71]
	v_mfma_f32_16x16x32_bf16 v[68:71], v[28:31], v[120:123], v[148:151]
	v_mfma_f32_16x16x32_bf16 v[104:107], v[32:35], v[132:135], v[68:71]
	v_mfma_f32_16x16x32_bf16 v[68:71], v[20:23], v[222:225], v[152:155]
	v_mfma_f32_16x16x32_bf16 v[96:99], v[24:27], v[226:229], v[68:71]
	v_mfma_f32_16x16x32_bf16 v[68:71], v[28:31], v[222:225], v[156:159]
	v_mfma_f32_16x16x32_bf16 v[92:95], v[32:35], v[226:229], v[68:71]
	v_mfma_f32_16x16x32_bf16 v[68:71], v[20:23], v[230:233], v[170:173]
	v_mfma_f32_16x16x32_bf16 v[4:7], v[20:23], v[238:241], v[4:7]
	v_mfma_f32_16x16x32_bf16 v[84:87], v[24:27], v[234:237], v[68:71]
	v_mfma_f32_16x16x32_bf16 v[68:71], v[28:31], v[230:233], v[174:177]
	v_mfma_f32_16x16x32_bf16 v[72:75], v[24:27], v[242:245], v[4:7]
	v_mfma_f32_16x16x32_bf16 v[4:7], v[28:31], v[238:241], v[8:11]
	v_mfma_f32_16x16x32_bf16 v[80:83], v[32:35], v[234:237], v[68:71]
	v_mfma_f32_16x16x32_bf16 v[68:71], v[32:35], v[242:245], v[4:7]
	v_mfma_f32_16x16x32_bf16 v[4:7], v[206:209], v[120:123], v[12:15]
	v_mfma_f32_16x16x32_bf16 v[32:35], v[210:213], v[132:135], v[4:7]
	v_mfma_f32_16x16x32_bf16 v[4:7], v[214:217], v[120:123], v[16:19]
	v_mfma_f32_16x16x32_bf16 v[28:31], v[218:221], v[132:135], v[4:7]
	v_mfma_f32_16x16x32_bf16 v[4:7], v[206:209], v[222:225], v[178:181]
	v_mfma_f32_16x16x32_bf16 v[24:27], v[210:213], v[226:229], v[4:7]
	v_mfma_f32_16x16x32_bf16 v[4:7], v[214:217], v[222:225], v[182:185]
	v_mfma_f32_16x16x32_bf16 v[20:23], v[218:221], v[226:229], v[4:7]
	v_mfma_f32_16x16x32_bf16 v[4:7], v[206:209], v[230:233], v[186:189]
	v_mfma_f32_16x16x32_bf16 v[16:19], v[210:213], v[234:237], v[4:7]
	v_mfma_f32_16x16x32_bf16 v[4:7], v[214:217], v[230:233], v[190:193]
	v_mfma_f32_16x16x32_bf16 v[12:15], v[218:221], v[234:237], v[4:7]
	v_mfma_f32_16x16x32_bf16 v[4:7], v[206:209], v[238:241], v[194:197]
	v_mfma_f32_16x16x32_bf16 v[8:11], v[210:213], v[242:245], v[4:7]
	v_mfma_f32_16x16x32_bf16 v[4:7], v[214:217], v[238:241], v[198:201]
	v_mfma_f32_16x16x32_bf16 v[4:7], v[218:221], v[242:245], v[4:7]
	s_barrier
	s_setprio 0
	s_add_u32 s77, s26, 0x200
	s_addc_u32 s79, s27, 0
	s_mov_b32 s80, 0
